# DIFF attention item: hand-scheduled two-stage pipelined loop (softmax of one map overlapped with QK/PV MFMAs of the other), 3-deep LDS ring, near-band bias and shift-tile rebuild out of line; original
# speedup vs baseline: 1.0672x; 1.0615x over previous
; #define MFMA(a, b, c) __builtin_amdgcn_mfma_f32_32x32x16_bf16((a), (b), (c), 0, 0, 0)
; DI unsigned pk2(float lo, float hi) { f32x2 v = {lo, hi}; b16x2 r = __builtin_convertvector(v, b16x2); return __builtin_bit_cast(unsigned, r); }
; #define LDS_BARRIER() asm volatile("s_waitcnt lgkmcnt(0)\n\ts_barrier" ::: "memory")
; template <int MODE>
; DI void attn_item(const Params& p, int layer, int bh, int qb, char* lds) {
;     ...
;         auto smpass = [&]() {
;           ps = 0.f;
; #pragma unroll
;           for (int sub = 0; sub < 2; ++sub)
; #pragma unroll
;             for (int ks = 0; ks < 2; ++ks)
; #pragma unroll
;               for (int i = 0; i < 4; ++i) {
;                 const float p0 = __builtin_amdgcn_exp2f(s[sub][8 * ks + 2 * i]), p1 = __builtin_amdgcn_exp2f(s[sub][8 * ks + 2 * i + 1]);
;                 ps += p0 + p1; pk[mp][sub][ks][i] = pk2(p0, p1);
;               }
;         };
;         if (first) rebase();
;         smpass();
;         if (!first && __any(!(ps <= PSLIM))) { rebase(); smpass(); }
;         l[mp] += ps;
;         __builtin_amdgcn_sched_barrier(0);
;       }
; #pragma unroll
;       for (int sub = 0; sub < 2; ++sub) {
;         s16x4 vv[8];
;         if (NMAP == 1) {
; #pragma unroll
;           for (int i = 0; i < 8; ++i) vv[i] = vpre[sub * 8 + i];
;         } else {
;           if (sub == 0) trread8<0>(vaddr, vv); else trread8<32 * VSTR>(vaddr, vv);
;         }
;         __builtin_amdgcn_s_setprio(1);
; #pragma unroll
;         for (int ks = 0; ks < 2; ++ks) {
; #pragma unroll
;           for (int dt = 0; dt < 2; ++dt) {
;             s16x4 lo = vv[ks * 4 + dt * 2], hi = vv[ks * 4 + dt * 2 + 1];
;             bf16x8 vf = __builtin_shufflevector(lo, hi, 0, 1, 2, 3, 4, 5, 6, 7);
; #pragma unroll
;             for (int mp = 0; mp < NMAP; ++mp) O[mp][dt] = MFMA(vf, __builtin_bit_cast(bf16x8, pk[mp][sub][ks]), O[mp][dt]);
;           }
;         }
;         __builtin_amdgcn_s_setprio(0);
;         __builtin_amdgcn_sched_barrier(0);
;       }
;     ...
;   for (int t = 0; t < nt; t += 2) {
;     if (t + 2 < nt) gload(kt0 + t + 2, rkA, rvA);
;     compute(t, 0);
;     if (t + 1 < nt) lstore(1, rkB, rvB);
;     LDS_BARRIER();
.Lmla_loop:
	ds_read_b128 v[176:179], v200 offset:27648
	ds_read_b128 v[180:183], v200 offset:27680
	ds_read_b128 v[222:225], v200 offset:27712
	s_waitcnt vmcnt(0)
	ds_write_b128 v202, v[96:99] offset:2048
	ds_write_b64 v203, v[100:101] offset:2048
	ds_write_b128 v207, v[188:191] offset:40960
	buffer_load_dwordx4 v[230:233], v187, s[20:23], s62 offen
	buffer_load_dwordx2 v[234:235], v205, s[20:23], s62 offen
	buffer_load_dwordx4 v[236:239], v187, s[12:15], s29 offen
	s_add_u32 s62, s62, 0x3000
	s_add_u32 s29, s29, 0x2000
	v_exp_f32_e32 v0, v64
	v_exp_f32_e32 v1, v65
	v_exp_f32_e32 v2, v66
	v_exp_f32_e32 v3, v67
	v_add_f32_e32 v10, v0, v1
	v_cvt_pk_bf16_f32 v160, v0, v1
	s_waitcnt lgkmcnt(5)
	v_mfma_f32_32x32x16_bf16 v[128:143], v[176:179], v[104:107], v[48:63]
	ds_read_b128 v[226:229], v200 offset:27744
	s_waitcnt lgkmcnt(5)
	v_mfma_f32_32x32x16_bf16 v[128:143], v[180:183], v[108:111], v[128:143]
	ds_read_b64_tr_b16 v[176:177], v201 offset:15360
	ds_read_b64_tr_b16 v[178:179], v201 offset:16896
	v_add_f32_e32 v10, v10, v2
	v_add_f32_e32 v10, v10, v3
	v_cvt_pk_bf16_f32 v161, v2, v3
	s_waitcnt lgkmcnt(6)
	v_mfma_f32_32x32x16_bf16 v[128:143], v[222:225], v[112:115], v[128:143]
	ds_read_b64_tr_b16 v[180:181], v201 offset:15424
	ds_read_b64_tr_b16 v[182:183], v201 offset:16960
	v_exp_f32_e32 v6, v68
	v_exp_f32_e32 v7, v69
	v_exp_f32_e32 v8, v70
	v_exp_f32_e32 v9, v71
	v_add_f32_e32 v10, v10, v6
	s_waitcnt lgkmcnt(4)
	v_mfma_f32_32x32x16_bf16 v[128:143], v[226:229], v[116:119], v[128:143]
	ds_read_b128 v[222:225], v200 offset:27776
	v_add_f32_e32 v10, v10, v7
	v_cvt_pk_bf16_f32 v162, v6, v7
	v_add_f32_e32 v10, v10, v8
	v_add_f32_e32 v10, v10, v9
	v_cvt_pk_bf16_f32 v163, v8, v9
	s_waitcnt lgkmcnt(3)
	s_nop 0
	v_mfma_f32_32x32x16_bf16 v[32:47], v[176:179], v[160:163], v[32:47]
	ds_read_b128 v[226:229], v200 offset:27808
	v_exp_f32_e32 v0, v72
	v_exp_f32_e32 v1, v73
	v_exp_f32_e32 v2, v74
	s_waitcnt lgkmcnt(2)
	v_mfma_f32_32x32x16_bf16 v[16:31], v[180:183], v[160:163], v[16:31]
	ds_read_b128 v[176:179], v200 offset:34304
	v_exp_f32_e32 v3, v75
	v_add_f32_e32 v11, v0, v1
	v_cvt_pk_bf16_f32 v164, v0, v1
	v_add_f32_e32 v11, v11, v2
	s_waitcnt lgkmcnt(2)
	v_mfma_f32_32x32x16_bf16 v[128:143], v[222:225], v[120:123], v[128:143]
	ds_read_b64_tr_b16 v[180:181], v201 offset:18432
	ds_read_b64_tr_b16 v[182:183], v201 offset:19968
	v_add_f32_e32 v11, v11, v3
	v_cvt_pk_bf16_f32 v165, v2, v3
	v_exp_f32_e32 v6, v76
	v_exp_f32_e32 v7, v77
	s_waitcnt lgkmcnt(3)
	v_mfma_f32_32x32x16_bf16 v[128:143], v[226:229], v[124:127], v[128:143]
	ds_read_b64_tr_b16 v[222:223], v201 offset:18496
	ds_read_b64_tr_b16 v[224:225], v201 offset:20032
	v_exp_f32_e32 v8, v78
	v_exp_f32_e32 v9, v79
	v_add_f32_e32 v11, v11, v6
	v_add_f32_e32 v11, v11, v7
	s_waitcnt lgkmcnt(4)
	v_mfma_f32_32x32x16_bf16 v[144:159], v[176:179], v[104:107], v[48:63]
	ds_read_b128 v[226:229], v200 offset:34336
	v_cvt_pk_bf16_f32 v166, v6, v7
	v_add_f32_e32 v11, v11, v8
	v_add_f32_e32 v11, v11, v9
	v_cvt_pk_bf16_f32 v167, v8, v9
	s_waitcnt lgkmcnt(3)
	s_nop 0
	v_mfma_f32_32x32x16_bf16 v[32:47], v[180:183], v[164:167], v[32:47]
	ds_read_b128 v[176:179], v200 offset:34368
	v_exp_f32_e32 v0, v80
	v_exp_f32_e32 v1, v81
	v_exp_f32_e32 v2, v82
	s_waitcnt lgkmcnt(2)
	v_mfma_f32_32x32x16_bf16 v[16:31], v[222:225], v[164:167], v[16:31]
	ds_read_b128 v[180:183], v200 offset:34400
	v_exp_f32_e32 v3, v83
	v_add_f32_e32 v12, v0, v1
	v_cvt_pk_bf16_f32 v168, v0, v1
	v_add_f32_e32 v12, v12, v2
	s_waitcnt lgkmcnt(2)
	v_mfma_f32_32x32x16_bf16 v[144:159], v[226:229], v[108:111], v[144:159]
	ds_read_b64_tr_b16 v[222:223], v201 offset:21504
	ds_read_b64_tr_b16 v[224:225], v201 offset:23040
	v_add_f32_e32 v12, v12, v3
	v_cvt_pk_bf16_f32 v169, v2, v3
	v_exp_f32_e32 v6, v84
	v_exp_f32_e32 v7, v85
	s_waitcnt lgkmcnt(3)
	v_mfma_f32_32x32x16_bf16 v[144:159], v[176:179], v[112:115], v[144:159]
	ds_read_b64_tr_b16 v[226:227], v201 offset:21568
	ds_read_b64_tr_b16 v[228:229], v201 offset:23104
	v_exp_f32_e32 v8, v86
	v_exp_f32_e32 v9, v87
	v_add_f32_e32 v12, v12, v6
	v_add_f32_e32 v12, v12, v7
	s_waitcnt lgkmcnt(4)
	v_mfma_f32_32x32x16_bf16 v[144:159], v[180:183], v[116:119], v[144:159]
	ds_read_b128 v[176:179], v200 offset:34432
	v_cvt_pk_bf16_f32 v170, v6, v7
	v_add_f32_e32 v12, v12, v8
	v_add_f32_e32 v12, v12, v9
	v_cvt_pk_bf16_f32 v171, v8, v9
	s_waitcnt lgkmcnt(3)
	s_nop 0
	v_mfma_f32_32x32x16_bf16 v[32:47], v[222:225], v[168:171], v[32:47]
	ds_read_b128 v[180:183], v200 offset:34464
	v_exp_f32_e32 v0, v88
	v_exp_f32_e32 v1, v89
	v_exp_f32_e32 v2, v90
	v_exp_f32_e32 v3, v91
	s_waitcnt lgkmcnt(2)
	v_mfma_f32_32x32x16_bf16 v[16:31], v[226:229], v[168:171], v[16:31]
	ds_read_b64_tr_b16 v[222:223], v201 offset:24576
	ds_read_b64_tr_b16 v[224:225], v201 offset:26112
	v_add_f32_e32 v13, v0, v1
	v_cvt_pk_bf16_f32 v172, v0, v1
	v_add_f32_e32 v13, v13, v2
	v_add_f32_e32 v13, v13, v3
	v_cvt_pk_bf16_f32 v173, v2, v3
	s_waitcnt lgkmcnt(3)
	v_mfma_f32_32x32x16_bf16 v[144:159], v[176:179], v[120:123], v[144:159]
	ds_read_b64_tr_b16 v[226:227], v201 offset:24640
	ds_read_b64_tr_b16 v[228:229], v201 offset:26176
	v_exp_f32_e32 v6, v92
	v_exp_f32_e32 v7, v93
	v_exp_f32_e32 v8, v94
	v_exp_f32_e32 v9, v95
	v_add_f32_e32 v13, v13, v6
	s_waitcnt lgkmcnt(4)
	v_mfma_f32_32x32x16_bf16 v[144:159], v[180:183], v[124:127], v[144:159]
	v_add_f32_e32 v13, v13, v7
	v_cvt_pk_bf16_f32 v174, v6, v7
	v_add_f32_e32 v13, v13, v8
	v_add_f32_e32 v13, v13, v9
	v_cvt_pk_bf16_f32 v175, v8, v9
	s_waitcnt lgkmcnt(2)
	s_nop 0
	v_mfma_f32_32x32x16_bf16 v[32:47], v[222:225], v[172:175], v[32:47]
	s_waitcnt lgkmcnt(0)
	v_mfma_f32_32x32x16_bf16 v[16:31], v[226:229], v[172:175], v[16:31]
	v_add_f32_e32 v10, v10, v11
	v_add_f32_e32 v12, v12, v13
	v_add_f32_e32 v10, v10, v12
	v_add_f32_e32 v192, v192, v10
	v_max_f32_e32 v193, v193, v10
	s_waitcnt lgkmcnt(0)
	s_barrier
; #define MFMA(a, b, c) __builtin_amdgcn_mfma_f32_32x32x16_bf16((a), (b), (c), 0, 0, 0)
; DI unsigned pk2(float lo, float hi) { f32x2 v = {lo, hi}; b16x2 r = __builtin_convertvector(v, b16x2); return __builtin_bit_cast(unsigned, r); }
; #define LDS_BARRIER() asm volatile("s_waitcnt lgkmcnt(0)\n\ts_barrier" ::: "memory")
; template <int MODE>
; DI void attn_item(const Params& p, int layer, int bh, int qb, char* lds) {
;     ...
;         auto smpass = [&]() {
;           ps = 0.f;
; #pragma unroll
;           for (int sub = 0; sub < 2; ++sub)
; #pragma unroll
;             for (int ks = 0; ks < 2; ++ks)
; #pragma unroll
;               for (int i = 0; i < 4; ++i) {
;                 const float p0 = __builtin_amdgcn_exp2f(s[sub][8 * ks + 2 * i]), p1 = __builtin_amdgcn_exp2f(s[sub][8 * ks + 2 * i + 1]);
;                 ps += p0 + p1; pk[mp][sub][ks][i] = pk2(p0, p1);
;               }
;         };
;         if (first) rebase();
;         smpass();
;         if (!first && __any(!(ps <= PSLIM))) { rebase(); smpass(); }
;         l[mp] += ps;
;         __builtin_amdgcn_sched_barrier(0);
;       }
; #pragma unroll
;       for (int sub = 0; sub < 2; ++sub) {
;         s16x4 vv[8];
;         if (NMAP == 1) {
; #pragma unroll
;           for (int i = 0; i < 8; ++i) vv[i] = vpre[sub * 8 + i];
;         } else {
;           if (sub == 0) trread8<0>(vaddr, vv); else trread8<32 * VSTR>(vaddr, vv);
;         }
;         __builtin_amdgcn_s_setprio(1);
; #pragma unroll
;         for (int ks = 0; ks < 2; ++ks) {
; #pragma unroll
;           for (int dt = 0; dt < 2; ++dt) {
;             s16x4 lo = vv[ks * 4 + dt * 2], hi = vv[ks * 4 + dt * 2 + 1];
;             bf16x8 vf = __builtin_shufflevector(lo, hi, 0, 1, 2, 3, 4, 5, 6, 7);
; #pragma unroll
;             for (int mp = 0; mp < NMAP; ++mp) O[mp][dt] = MFMA(vf, __builtin_bit_cast(bf16x8, pk[mp][sub][ks]), O[mp][dt]);
;           }
;         }
;         __builtin_amdgcn_s_setprio(0);
;         __builtin_amdgcn_sched_barrier(0);
;       }
;     ...
;     if (t + 1 >= nt) break;
;     if (t + 3 < nt) gload(kt0 + t + 3, rkB, rvB);
;     compute(t + 1, 1);
;     if (t + 2 < nt) lstore(0, rkA, rvA);
;     LDS_BARRIER();
	ds_read_b128 v[176:179], v200 offset:2048
	ds_read_b128 v[180:183], v200 offset:2080
	ds_read_b128 v[222:225], v200 offset:2112
	s_waitcnt vmcnt(0)
	ds_write_b128 v202, v[230:233] offset:27648
	ds_write_b64 v203, v[234:235] offset:27648
	ds_write_b128 v207, v[236:239] offset:15360
	buffer_load_dwordx4 v[96:99], v187, s[20:23], s62 offen
	buffer_load_dwordx2 v[100:101], v205, s[20:23], s62 offen
	buffer_load_dwordx4 v[188:191], v187, s[12:15], s29 offen
	s_add_u32 s62, s62, 0x3000
	s_add_u32 s29, s29, 0x2000
	v_exp_f32_e32 v0, v128
	v_exp_f32_e32 v1, v129
	v_exp_f32_e32 v2, v130
	v_exp_f32_e32 v3, v131
	v_add_f32_e32 v10, v0, v1
	v_cvt_pk_bf16_f32 v160, v0, v1
	s_waitcnt lgkmcnt(5)
	v_mfma_f32_32x32x16_bf16 v[64:79], v[176:179], v[104:107], v[48:63]
	ds_read_b128 v[226:229], v200 offset:2144
	s_waitcnt lgkmcnt(5)
	v_mfma_f32_32x32x16_bf16 v[64:79], v[180:183], v[108:111], v[64:79]
	ds_read_b64_tr_b16 v[176:177], v201 offset:40960
	ds_read_b64_tr_b16 v[178:179], v201 offset:42496
	v_add_f32_e32 v10, v10, v2
	v_add_f32_e32 v10, v10, v3
	v_cvt_pk_bf16_f32 v161, v2, v3
	s_waitcnt lgkmcnt(6)
	v_mfma_f32_32x32x16_bf16 v[64:79], v[222:225], v[112:115], v[64:79]
	ds_read_b64_tr_b16 v[180:181], v201 offset:41024
	ds_read_b64_tr_b16 v[182:183], v201 offset:42560
	v_exp_f32_e32 v6, v132
	v_exp_f32_e32 v7, v133
	v_exp_f32_e32 v8, v134
	v_exp_f32_e32 v9, v135
	v_add_f32_e32 v10, v10, v6
	s_waitcnt lgkmcnt(4)
	v_mfma_f32_32x32x16_bf16 v[64:79], v[226:229], v[116:119], v[64:79]
	ds_read_b128 v[222:225], v200 offset:2176
	v_add_f32_e32 v10, v10, v7
	v_cvt_pk_bf16_f32 v162, v6, v7
	v_add_f32_e32 v10, v10, v8
	v_add_f32_e32 v10, v10, v9
	v_cvt_pk_bf16_f32 v163, v8, v9
	s_waitcnt lgkmcnt(3)
	s_nop 0
	v_mfma_f32_32x32x16_bf16 v[32:47], v[176:179], v[160:163], v[32:47]
	ds_read_b128 v[226:229], v200 offset:2208
	v_exp_f32_e32 v0, v136
	v_exp_f32_e32 v1, v137
	v_exp_f32_e32 v2, v138
	s_waitcnt lgkmcnt(2)
	v_mfma_f32_32x32x16_bf16 v[16:31], v[180:183], v[160:163], v[16:31]
	ds_read_b128 v[176:179], v200 offset:8704
	v_exp_f32_e32 v3, v139
	v_add_f32_e32 v11, v0, v1
	v_cvt_pk_bf16_f32 v164, v0, v1
	v_add_f32_e32 v11, v11, v2
	s_waitcnt lgkmcnt(2)
	v_mfma_f32_32x32x16_bf16 v[64:79], v[222:225], v[120:123], v[64:79]
	ds_read_b64_tr_b16 v[180:181], v201 offset:44032
	ds_read_b64_tr_b16 v[182:183], v201 offset:45568
	v_add_f32_e32 v11, v11, v3
	v_cvt_pk_bf16_f32 v165, v2, v3
	v_exp_f32_e32 v6, v140
	v_exp_f32_e32 v7, v141
	s_waitcnt lgkmcnt(3)
	v_mfma_f32_32x32x16_bf16 v[64:79], v[226:229], v[124:127], v[64:79]
	ds_read_b64_tr_b16 v[222:223], v201 offset:44096
	ds_read_b64_tr_b16 v[224:225], v201 offset:45632
	v_exp_f32_e32 v8, v142
	v_exp_f32_e32 v9, v143
	v_add_f32_e32 v11, v11, v6
	v_add_f32_e32 v11, v11, v7
	s_waitcnt lgkmcnt(4)
	v_mfma_f32_32x32x16_bf16 v[80:95], v[176:179], v[104:107], v[48:63]
	ds_read_b128 v[226:229], v200 offset:8736
	v_cvt_pk_bf16_f32 v166, v6, v7
	v_add_f32_e32 v11, v11, v8
	v_add_f32_e32 v11, v11, v9
	v_cvt_pk_bf16_f32 v167, v8, v9
	s_waitcnt lgkmcnt(3)
	s_nop 0
	v_mfma_f32_32x32x16_bf16 v[32:47], v[180:183], v[164:167], v[32:47]
	ds_read_b128 v[176:179], v200 offset:8768
	v_exp_f32_e32 v0, v144
	v_exp_f32_e32 v1, v145
	v_exp_f32_e32 v2, v146
	s_waitcnt lgkmcnt(2)
	v_mfma_f32_32x32x16_bf16 v[16:31], v[222:225], v[164:167], v[16:31]
	ds_read_b128 v[180:183], v200 offset:8800
	v_exp_f32_e32 v3, v147
	v_add_f32_e32 v12, v0, v1
	v_cvt_pk_bf16_f32 v168, v0, v1
	v_add_f32_e32 v12, v12, v2
	s_waitcnt lgkmcnt(2)
	v_mfma_f32_32x32x16_bf16 v[80:95], v[226:229], v[108:111], v[80:95]
	ds_read_b64_tr_b16 v[222:223], v201 offset:47104
	ds_read_b64_tr_b16 v[224:225], v201 offset:48640
	v_add_f32_e32 v12, v12, v3
	v_cvt_pk_bf16_f32 v169, v2, v3
	v_exp_f32_e32 v6, v148
	v_exp_f32_e32 v7, v149
	s_waitcnt lgkmcnt(3)
	v_mfma_f32_32x32x16_bf16 v[80:95], v[176:179], v[112:115], v[80:95]
	ds_read_b64_tr_b16 v[226:227], v201 offset:47168
	ds_read_b64_tr_b16 v[228:229], v201 offset:48704
	v_exp_f32_e32 v8, v150
	v_exp_f32_e32 v9, v151
	v_add_f32_e32 v12, v12, v6
	v_add_f32_e32 v12, v12, v7
	s_waitcnt lgkmcnt(4)
	v_mfma_f32_32x32x16_bf16 v[80:95], v[180:183], v[116:119], v[80:95]
	ds_read_b128 v[176:179], v200 offset:8832
	v_cvt_pk_bf16_f32 v170, v6, v7
	v_add_f32_e32 v12, v12, v8
	v_add_f32_e32 v12, v12, v9
	v_cvt_pk_bf16_f32 v171, v8, v9
	s_waitcnt lgkmcnt(3)
	s_nop 0
	v_mfma_f32_32x32x16_bf16 v[32:47], v[222:225], v[168:171], v[32:47]
	ds_read_b128 v[180:183], v200 offset:8864
	v_exp_f32_e32 v0, v152
	v_exp_f32_e32 v1, v153
	v_exp_f32_e32 v2, v154
	v_exp_f32_e32 v3, v155
	s_waitcnt lgkmcnt(2)
	v_mfma_f32_32x32x16_bf16 v[16:31], v[226:229], v[168:171], v[16:31]
	ds_read_b64_tr_b16 v[222:223], v201 offset:50176
	ds_read_b64_tr_b16 v[224:225], v201 offset:51712
	v_add_f32_e32 v13, v0, v1
	v_cvt_pk_bf16_f32 v172, v0, v1
	v_add_f32_e32 v13, v13, v2
	v_add_f32_e32 v13, v13, v3
	v_cvt_pk_bf16_f32 v173, v2, v3
	s_waitcnt lgkmcnt(3)
	v_mfma_f32_32x32x16_bf16 v[80:95], v[176:179], v[120:123], v[80:95]
	ds_read_b64_tr_b16 v[226:227], v201 offset:50240
	ds_read_b64_tr_b16 v[228:229], v201 offset:51776
	v_exp_f32_e32 v6, v156
	v_exp_f32_e32 v7, v157
	v_exp_f32_e32 v8, v158
	v_exp_f32_e32 v9, v159
	v_add_f32_e32 v13, v13, v6
	s_waitcnt lgkmcnt(4)
	v_mfma_f32_32x32x16_bf16 v[80:95], v[180:183], v[124:127], v[80:95]
	v_add_f32_e32 v13, v13, v7
	v_cvt_pk_bf16_f32 v174, v6, v7
	v_add_f32_e32 v13, v13, v8
	v_add_f32_e32 v13, v13, v9
	v_cvt_pk_bf16_f32 v175, v8, v9
	s_waitcnt lgkmcnt(2)
	s_nop 0
	v_mfma_f32_32x32x16_bf16 v[32:47], v[222:225], v[172:175], v[32:47]
	s_waitcnt lgkmcnt(0)
	v_mfma_f32_32x32x16_bf16 v[16:31], v[226:229], v[172:175], v[16:31]
	v_add_f32_e32 v10, v10, v11
	v_add_f32_e32 v12, v12, v13
	v_add_f32_e32 v10, v10, v12
	v_add_f32_e32 v192, v192, v10
	v_max_f32_e32 v193, v193, v10
	s_add_u32 s28, s28, 2
	s_cmpk_lt_u32 s28, 0x80
	s_waitcnt lgkmcnt(0)
	s_barrier
; DI unsigned pk2(float lo, float hi) { f32x2 v = {lo, hi}; b16x2 r = __builtin_convertvector(v, b16x2); return __builtin_bit_cast(unsigned, r); }
; DI float bflo(unsigned w) { return __uint_as_float(w << 16); }
; DI float bfhi(unsigned w) { return __uint_as_float(w & 0xffff0000u); }
; template <int MODE>
; DI void attn_item(const Params& p, int layer, int bh, int qb, char* lds) {
;     ...
;   __syncthreads();
;   const size_t trow = (size_t)b * S + q0w + l32;
;   const u16* grow = (const u16*)(p.ws + OFF_H) + trow * DIN + C_GATE + ocol;
;   u16* orow = (u16*)(p.ws + OFF_OB) + trow * DM + ocol;
;   float inv0 = 1.f / xchg_sum(l[0]);
;   if (MODE == 1) {
;     const float* lm = (const float*)(p.ws + OFF_LAM);
;     const float lam = lm[layer], post = lm[4 + layer];
;     const float inv1 = lam / xchg_sum(l[1]);
;     float ss = 0.f;
; #pragma unroll
;     for (int dt = 0; dt < 2; ++dt)
; #pragma unroll
;       for (int r = 0; r < 16; ++r) { float v = O[0][dt][r] * inv0 - O[NMAP - 1][dt][r] * inv1; O[0][dt][r] = v; ss += v * v; }
;     ss = xchg_sum(ss);
;     inv0 = rsqrtf(ss * (1.f / 64.f) + 1e-6f) * post;
;   }
; #pragma unroll
;   for (int dt = 0; dt < 2; ++dt)
; #pragma unroll
;     for (int g = 0; g < 4; ++g) {
;       const int d = 32 * dt + 8 * g + 4 * hh;
;       u32x2 gw = *(const u32x2*)(grow + d);
;       float v0 = O[0][dt][4 * g + 0] * inv0, v1 = O[0][dt][4 * g + 1] * inv0, v2 = O[0][dt][4 * g + 2] * inv0, v3 = O[0][dt][4 * g + 3] * inv0;
;       if (MODE == 1) { const float* sl = p.subln + layer * 64 + d; v0 *= sl[0]; v1 *= sl[1]; v2 *= sl[2]; v3 *= sl[3]; }
;       v0 *= bflo(gw[0]); v1 *= bfhi(gw[0]); v2 *= bflo(gw[1]); v3 *= bfhi(gw[1]);
;       u32x2 ow = {pk2(v0, v1), pk2(v2, v3)};
;     ...
;       if (MODE == PROBE_ZERO_MODE) { ow[0] = 0u; ow[1] = 0u; }
;     ...
;       *(u32x2*)(orow + d) = ow;
;     }
	s_cbranch_scc1 .Lmla_loop
	s_waitcnt vmcnt(0)
	s_lshl_b64 s[6:7], s[10:11], 13
	v_ashrrev_i32_e32 v187, 31, v186
	v_lshl_add_u64 v[0:1], s[6:7], 0, v[186:187]
	v_or_b32_e32 v0, v0, v204
	v_mov_b32_e32 v2, s34
	v_mov_b32_e32 v3, s35
	v_mad_u64_u32 v[2:3], s[6:7], v0, s64, v[2:3]
	v_mad_i32_i24 v3, v1, s64, v3
	s_lshl_b32 s4, s52, 7
	v_lshl_add_u32 v12, v206, 1, s4
	v_mov_b32_e32 v13, 0
	v_lshl_add_u64 v[6:7], v[2:3], 0, v[12:13]
	s_mov_b64 s[6:7], 0x6058ec0
	v_lshl_add_u64 v[6:7], v[6:7], 0, s[6:7]
	global_load_dwordx2 v[64:65], v[6:7], off offset:0
	global_load_dwordx2 v[66:67], v[6:7], off offset:16
	global_load_dwordx2 v[68:69], v[6:7], off offset:32
	global_load_dwordx2 v[70:71], v[6:7], off offset:48
	global_load_dwordx2 v[72:73], v[6:7], off offset:64
	global_load_dwordx2 v[74:75], v[6:7], off offset:80
	global_load_dwordx2 v[76:77], v[6:7], off offset:96
	global_load_dwordx2 v[78:79], v[6:7], off offset:112
	v_readlane_b32 s6, v254, 49
	v_readlane_b32 s7, v254, 50
	v_lshlrev_b64 v[0:1], 11, v[0:1]
	s_nop 0
	v_lshl_add_u64 v[0:1], s[6:7], 0, v[0:1]
	v_lshl_add_u64 v[8:9], v[0:1], 0, v[12:13]
	v_cmp_nge_f32_e32 vcc, s94, v193
	s_nop 0
	s_cmp_lg_u64 vcc, 0
	s_cselect_b32 s24, 1, 0
	v_mov_b32_e32 v196, s24
	v_lshrrev_b32_e32 v197, 6, v184
	v_lshlrev_b32_e32 v197, 2, v197
	ds_write_b32 v197, v196 offset:0
	s_waitcnt lgkmcnt(0)
	s_barrier
	v_mov_b32_e32 v197, 0
	ds_read_b128 v[176:179], v197 offset:0
	ds_read_b128 v[180:183], v197 offset:16
	v_mov_b32_e32 v2, v192
	s_nop 1
	v_permlane32_swap_b32_e32 v192, v2
	v_add_f32_e32 v2, v192, v2
	v_div_scale_f32 v3, s[4:5], v2, v2, 1.0
	v_rcp_f32_e32 v4, v3
	s_nop 0
	v_fma_f32 v10, -v3, v4, 1.0
	v_fmac_f32_e32 v4, v10, v4
	v_div_scale_f32 v10, vcc, 1.0, v2, 1.0
	v_mul_f32_e32 v11, v10, v4
	v_fma_f32 v12, -v3, v11, v10
	v_fmac_f32_e32 v11, v12, v4
	v_fma_f32 v3, -v3, v11, v10
	s_nop 1
	v_div_fmas_f32 v3, v3, v4, v11
	v_div_fixup_f32 v2, v3, v2, 1.0
	s_waitcnt lgkmcnt(0)
	v_or3_b32 v196, v176, v177, v178
	v_or3_b32 v196, v196, v179, v180
	v_or3_b32 v196, v196, v181, v182
	v_or_b32_e32 v196, v196, v183
	s_nop 0
	v_readfirstlane_b32 s24, v196
	s_barrier
	s_cmp_lg_u32 s24, 0
	s_cbranch_scc1 .Lmla_slow
	s_waitcnt vmcnt(0)
	v_mul_f32_e32 v32, v32, v2
	v_mul_f32_e32 v33, v33, v2
	v_mul_f32_e32 v34, v34, v2
	v_mul_f32_e32 v35, v35, v2
	v_lshlrev_b32_e32 v196, 16, v64
	v_and_b32_e32 v197, 0xffff0000, v64
	v_mul_f32_e32 v32, v32, v196
	v_mul_f32_e32 v33, v33, v197
	v_lshlrev_b32_e32 v196, 16, v65
	v_and_b32_e32 v197, 0xffff0000, v65
	v_mul_f32_e32 v34, v34, v196
	v_mul_f32_e32 v35, v35, v197
	v_cvt_pk_bf16_f32 v32, v32, v33
	v_cvt_pk_bf16_f32 v33, v34, v35
	global_store_dwordx2 v[8:9], v[32:33], off offset:0
	v_mul_f32_e32 v36, v36, v2
	v_mul_f32_e32 v37, v37, v2
	v_mul_f32_e32 v38, v38, v2
	v_mul_f32_e32 v39, v39, v2
	v_lshlrev_b32_e32 v196, 16, v66
	v_and_b32_e32 v197, 0xffff0000, v66
	v_mul_f32_e32 v36, v36, v196
	v_mul_f32_e32 v37, v37, v197
	v_lshlrev_b32_e32 v196, 16, v67
	v_and_b32_e32 v197, 0xffff0000, v67
	v_mul_f32_e32 v38, v38, v196
	v_mul_f32_e32 v39, v39, v197
	v_cvt_pk_bf16_f32 v36, v36, v37
	v_cvt_pk_bf16_f32 v37, v38, v39
	global_store_dwordx2 v[8:9], v[36:37], off offset:16
	v_mul_f32_e32 v40, v40, v2
	v_mul_f32_e32 v41, v41, v2
	v_mul_f32_e32 v42, v42, v2
	v_mul_f32_e32 v43, v43, v2
	v_lshlrev_b32_e32 v196, 16, v68
	v_and_b32_e32 v197, 0xffff0000, v68
	v_mul_f32_e32 v40, v40, v196
	v_mul_f32_e32 v41, v41, v197
	v_lshlrev_b32_e32 v196, 16, v69
	v_and_b32_e32 v197, 0xffff0000, v69
	v_mul_f32_e32 v42, v42, v196
	v_mul_f32_e32 v43, v43, v197
	v_cvt_pk_bf16_f32 v40, v40, v41
	v_cvt_pk_bf16_f32 v41, v42, v43
	global_store_dwordx2 v[8:9], v[40:41], off offset:32
	v_mul_f32_e32 v44, v44, v2
	v_mul_f32_e32 v45, v45, v2
	v_mul_f32_e32 v46, v46, v2
	v_mul_f32_e32 v47, v47, v2
	v_lshlrev_b32_e32 v196, 16, v70
	v_and_b32_e32 v197, 0xffff0000, v70
	v_mul_f32_e32 v44, v44, v196
	v_mul_f32_e32 v45, v45, v197
	v_lshlrev_b32_e32 v196, 16, v71
	v_and_b32_e32 v197, 0xffff0000, v71
	v_mul_f32_e32 v46, v46, v196
	v_mul_f32_e32 v47, v47, v197
	v_cvt_pk_bf16_f32 v44, v44, v45
	v_cvt_pk_bf16_f32 v45, v46, v47
	global_store_dwordx2 v[8:9], v[44:45], off offset:48
	v_mul_f32_e32 v16, v16, v2
	v_mul_f32_e32 v17, v17, v2
	v_mul_f32_e32 v18, v18, v2
	v_mul_f32_e32 v19, v19, v2
	v_lshlrev_b32_e32 v196, 16, v72
	v_and_b32_e32 v197, 0xffff0000, v72
	v_mul_f32_e32 v16, v16, v196
	v_mul_f32_e32 v17, v17, v197
	v_lshlrev_b32_e32 v196, 16, v73
	v_and_b32_e32 v197, 0xffff0000, v73
	v_mul_f32_e32 v18, v18, v196
	v_mul_f32_e32 v19, v19, v197
	v_cvt_pk_bf16_f32 v16, v16, v17
	v_cvt_pk_bf16_f32 v17, v18, v19
	global_store_dwordx2 v[8:9], v[16:17], off offset:64
	v_mul_f32_e32 v20, v20, v2
	v_mul_f32_e32 v21, v21, v2
	v_mul_f32_e32 v22, v22, v2
	v_mul_f32_e32 v23, v23, v2
	v_lshlrev_b32_e32 v196, 16, v74
	v_and_b32_e32 v197, 0xffff0000, v74
	v_mul_f32_e32 v20, v20, v196
	v_mul_f32_e32 v21, v21, v197
	v_lshlrev_b32_e32 v196, 16, v75
	v_and_b32_e32 v197, 0xffff0000, v75
	v_mul_f32_e32 v22, v22, v196
	v_mul_f32_e32 v23, v23, v197
	v_cvt_pk_bf16_f32 v20, v20, v21
	v_cvt_pk_bf16_f32 v21, v22, v23
	global_store_dwordx2 v[8:9], v[20:21], off offset:80
	v_mul_f32_e32 v24, v24, v2
	v_mul_f32_e32 v25, v25, v2
	v_mul_f32_e32 v26, v26, v2
	v_mul_f32_e32 v27, v27, v2
	v_lshlrev_b32_e32 v196, 16, v76
	v_and_b32_e32 v197, 0xffff0000, v76
	v_mul_f32_e32 v24, v24, v196
	v_mul_f32_e32 v25, v25, v197
	v_lshlrev_b32_e32 v196, 16, v77
	v_and_b32_e32 v197, 0xffff0000, v77
	v_mul_f32_e32 v26, v26, v196
	v_mul_f32_e32 v27, v27, v197
	v_cvt_pk_bf16_f32 v24, v24, v25
	v_cvt_pk_bf16_f32 v25, v26, v27
	global_store_dwordx2 v[8:9], v[24:25], off offset:96
	v_mul_f32_e32 v28, v28, v2
	v_mul_f32_e32 v29, v29, v2
	v_mul_f32_e32 v30, v30, v2
	v_mul_f32_e32 v31, v31, v2
	v_lshlrev_b32_e32 v196, 16, v78
	v_and_b32_e32 v197, 0xffff0000, v78
	v_mul_f32_e32 v28, v28, v196
	v_mul_f32_e32 v29, v29, v197
	v_lshlrev_b32_e32 v196, 16, v79
	v_and_b32_e32 v197, 0xffff0000, v79
	v_mul_f32_e32 v30, v30, v196
	v_mul_f32_e32 v31, v31, v197
	v_cvt_pk_bf16_f32 v28, v28, v29
	v_cvt_pk_bf16_f32 v29, v30, v31
	global_store_dwordx2 v[8:9], v[28:29], off offset:112
	s_branch .LBB0_321

; template <int MODE>
; DI void attn_item(const Params& p, int layer, int bh, int qb, char* lds) {
;     ...
;   bf16x8 qf[NMAP][QS];
;   {
;     const u16* qrow = Qg + (size_t)(q0w + l32) * qstr + hh * 8;
; #pragma unroll
;     for (int mp = 0; mp < NMAP; ++mp)
; #pragma unroll
;       for (int st = 0; st < QS; ++st) qf[mp][st] = *(const bf16x8*)(qrow + (mp * QS + st) * 16);
;   }
;   f32x16 O[NMAP][2]; float m = 0.f, l[NMAP];
; #pragma unroll
;   for (int mp = 0; mp < NMAP; ++mp) {
; #pragma unroll
;     for (int r = 0; r < 16; ++r) { O[mp][0][r] = 0.f; O[mp][1][r] = 0.f; }
;     l[mp] = 0.f;
;   }
;   if (MODE == 2) { m = p.sink[layer * 6 + hd] * LOG2E; l[0] = (hh == 0) ? 1.f : 0.f; }
;   int kt0 = 0, kt1 = S / 64;
;   if (MODE == 2) { kt0 = (q0 - 128) / 64; if (kt0 < 0) kt0 = 0; kt1 = (q0 + 384) / 64; if (kt1 > S / 64) kt1 = S / 64; }
;   const int nt = kt1 - kt0;
;   constexpr int KSTRG = MODE == 0 ? 96 : 64, VSTRG = 64;
;   u32x4 rkA[KCH], rvA[1], rkB[KCH], rvB[1];
;   const __amdgpu_buffer_rsrc_t krsrc = __builtin_amdgcn_make_buffer_rsrc((void*)Kg, 0, S * KSTRG * 2, 0x00027000);
;   const __amdgpu_buffer_rsrc_t vrsrc = __builtin_amdgcn_make_buffer_rsrc((void*)Vg, 0, S * VSTRG * 2, 0x00027000);
;   auto gload = [&](int kt, u32x4 (&rk)[KCH], u32x4 (&rv)[1]) {
;     const int ksoff = kt * (64 * KSTRG * 2), vsoff = kt * (64 * VSTRG * 2);
; #pragma unroll
;     for (int i = 0; i < KCH; ++i) if (tid + NTHR * i < KCHUNKS) rk[i] = __builtin_amdgcn_raw_buffer_load_b128(krsrc, tid * 16 + NTHR * 16 * i, ksoff, 0);
;     rv[0] = __builtin_amdgcn_raw_buffer_load_b128(vrsrc, tid * 16, vsoff, 0);
;   };
;   auto lstore = [&](int st, const u32x4 (&rk)[KCH], const u32x4 (&rv)[1]) {
;     char* Ks = stage0 + st * STAGE;
; #pragma unroll
;     for (int i = 0; i < KCH; ++i) { int c = tid + NTHR * i, row = c / KCPR, ch = c % KCPR; if (c < KCHUNKS) *(u32x4*)(Ks + row * KSTR + ch * 16) = rk[i]; }
;     { int row = tid >> 3, ch = tid & 7; *(u32x4*)(Ks + KBYTES + row * VSTR + ch * 16) = rv[0]; }
;   };
;   const unsigned vlane = (unsigned)((4 * hh + ((lane & 15) >> 2)) * VSTR + 32 * ((lane >> 4) & 1) + 8 * (lane & 3));
;   bf16x8 kaug, qaug;
;   { u32x4 tk = {hh == 0 ? 0x3F803F80u : 0u, 0u, 0u, 0u}; kaug = __builtin_bit_cast(bf16x8, tk); qaug = __builtin_bit_cast(bf16x8, (u32x4){0u, 0u, 0u, 0u}); }
;     ...
; #pragma unroll
;         for (int sub = 0; sub < 2; ++sub) {
; #pragma unroll
.LBB0_449:
	s_or_b64 exec, exec, s[8:9]
	s_add_i32 s6, s60, 0xfffffd00
	s_lshr_b32 s6, s6, 5
	s_and_b32 s6, s6, 0x7fffff8
	s_or_b32 s8, s6, s55
	s_lshl_b32 s6, s8, 11
	s_and_b32 s52, s6, 0x6000
	s_mul_i32 s6, s52, 0x15c0
	s_add_u32 s6, s34, s6
	s_addc_u32 s7, s35, 0
	s_lshl_b32 s9, s20, 7
	s_add_u32 s6, s6, s9
	s_waitcnt vmcnt(0)
	v_ashrrev_i32_e32 v0, 1, v6
	s_addc_u32 s7, s7, 0
	v_and_b32_e32 v7, 0xffffffe0, v0
	s_add_u32 s6, s6, 0x60583c0
	v_and_b32_e32 v203, 31, v6
	v_add_u32_e32 v168, s23, v7
	s_addc_u32 s7, s7, 0
	v_bfe_u32 v8, v6, 5, 1
	v_or_b32_e32 v2, v168, v203
	v_mov_b64_e32 v[0:1], s[6:7]
	v_mad_i64_i32 v[0:1], s[6:7], v2, s64, v[0:1]
	v_lshlrev_b32_e32 v4, 4, v8
	v_lshl_add_u64 v[10:11], v[0:1], 0, v[4:5]
	global_load_dwordx4 v[0:3], v[10:11], off
	global_load_dwordx4 v[120:123], v[10:11], off offset:32
	global_load_dwordx4 v[124:127], v[10:11], off offset:64
	global_load_dwordx4 v[128:131], v[10:11], off offset:96
	s_lshl_b32 s6, s8, 20
	v_readlane_b32 s8, v254, 41
	v_readlane_b32 s9, v254, 42
	s_add_u32 s8, s8, s6
	s_addc_u32 s7, s9, 0
	v_readlane_b32 s10, v254, 39
	v_readlane_b32 s11, v254, 40
	s_add_u32 s12, s10, s6
	s_addc_u32 s13, s11, 0
	s_and_b32 s9, s7, 0xffff
	v_lshlrev_b32_e32 v169, 4, v6
	s_waitcnt lgkmcnt(0)
	s_barrier
	s_and_b32 s13, s13, 0xffff
	s_mov_b32 s10, s14
	s_mov_b32 s11, s15
	s_and_b32 s49, s60, 3
	s_lshl_b32 s49, s49, 6
	v_and_b32_e32 v203, 31, v184
	v_bfe_u32 v197, v184, 5, 1
	v_lshlrev_b32_e32 v202, 2, v197
	v_mov_b32_e32 v198, 144
	v_mul_u32_u24_e32 v204, v203, v198
	v_lshl_add_u32 v204, v197, 4, v204
	v_bfe_u32 v198, v184, 2, 2
	v_lshl_add_u32 v198, v197, 2, v198
	v_mov_b32_e32 v199, 192
	v_mul_u32_u24_e32 v205, v198, v199
	v_bfe_u32 v198, v184, 4, 1
	v_lshl_add_u32 v205, v198, 5, v205
	v_and_b32_e32 v198, 3, v184
	v_lshl_add_u32 v205, v198, 3, v205
	v_lshrrev_b32_e32 v196, 3, v184
	v_and_b32_e32 v198, 7, v184
	v_mov_b32_e32 v199, 144
	v_mul_u32_u24_e32 v206, v196, v199
	v_lshl_add_u32 v206, v198, 4, v206
	v_mov_b32_e32 v199, 192
	v_mul_u32_u24_e32 v207, v196, v199
	v_lshl_add_u32 v207, v198, 4, v207
	v_lshlrev_b32_e32 v208, 4, v184
	v_cmp_eq_u32_e64 s[6:7], 0, v197
	v_sub_u32_e32 v196, v202, v203
	v_sub_u32_e32 v196, v196, v168
	v_add_u32_e32 v196, 0xe0, v196
	v_lshlrev_b32_e32 v209, 2, v196
	v_readfirstlane_b32 s4, v168
	s_nop 0
	s_add_i32 s24, s4, 0xffffff81
	s_ashr_i32 s24, s24, 6
	s_max_i32 s24, s24, 0
	s_add_i32 s25, s4, 0xde
	s_lshr_b32 s25, s25, 6
	buffer_load_dwordx4 v[132:135], v208, s[8:11], 0 offen
	buffer_load_dwordx4 v[136:139], v208, s[12:15], 0 offen
	s_movk_i32 s93, 0x2000
	buffer_load_dwordx4 v[140:143], v208, s[8:11], s93 offen
	v_mov_b32_e32 v144, 0
	v_mov_b32_e32 v145, 0
	v_mov_b32_e32 v146, 0
	v_mov_b32_e32 v147, 0
	ds_write_b128 v207, v[144:147] offset:54272
	ds_write_b128 v207, v[144:147] offset:60416
	s_waitcnt vmcnt(0)
	ds_write_b128 v206, v[132:135] offset:2048
	ds_write_b128 v207, v[136:139] offset:11264
	ds_write_b128 v206, v[140:143] offset:23552
	s_movk_i32 s93, 0x4000
	s_movk_i32 s28, 0x2000
	buffer_load_dwordx4 v[238:241], v208, s[8:11], s93 offen
	buffer_load_dwordx4 v[242:245], v208, s[12:15], s28 offen
	s_movk_i32 s93, 0x6000
	s_movk_i32 s28, 0x4000
	s_waitcnt lgkmcnt(0)
	s_barrier
	v_mov_b32_e32 v196, 0
	ds_read_b32 v210, v196 offset:384
	ds_read_b32 v211, v196 offset:1408
	ds_read_b128 v[222:225], v204 offset:2048
	ds_read_b128 v[226:229], v204 offset:2080
	ds_read_b128 v[230:233], v204 offset:6656
	ds_read_b128 v[234:237], v204 offset:6688
	s_waitcnt lgkmcnt(3)
	v_mfma_f32_32x32x16_bf16 v[88:103], v[222:225], v[0:3], 0
	s_waitcnt lgkmcnt(2)
	v_mfma_f32_32x32x16_bf16 v[88:103], v[226:229], v[120:123], v[88:103]
	s_waitcnt lgkmcnt(1)
	v_mfma_f32_32x32x16_bf16 v[104:119], v[230:233], v[0:3], 0
	s_waitcnt lgkmcnt(0)
	v_mfma_f32_32x32x16_bf16 v[104:119], v[234:237], v[120:123], v[104:119]
	v_mov_b32_e32 v56, 0
	v_mov_b32_e32 v57, 0
	v_mov_b32_e32 v58, 0
	v_mov_b32_e32 v59, 0
	v_mov_b32_e32 v60, 0
	v_mov_b32_e32 v61, 0
	v_mov_b32_e32 v62, 0
	v_mov_b32_e32 v63, 0
	v_mov_b32_e32 v64, 0
	v_mov_b32_e32 v65, 0
	v_mov_b32_e32 v66, 0
	v_mov_b32_e32 v67, 0
	v_mov_b32_e32 v68, 0
	v_mov_b32_e32 v69, 0
	v_mov_b32_e32 v70, 0
	v_mov_b32_e32 v71, 0
	v_mov_b32_e32 v24, 0
	v_mov_b32_e32 v25, 0
	v_mov_b32_e32 v26, 0
	v_mov_b32_e32 v27, 0
	v_mov_b32_e32 v28, 0
	v_mov_b32_e32 v29, 0
	v_mov_b32_e32 v30, 0
	v_mov_b32_e32 v31, 0
	v_mov_b32_e32 v32, 0
	v_mov_b32_e32 v33, 0
	v_mov_b32_e32 v34, 0
	v_mov_b32_e32 v35, 0
	v_mov_b32_e32 v36, 0
	v_mov_b32_e32 v37, 0
	v_mov_b32_e32 v38, 0
	v_mov_b32_e32 v39, 0
	v_mov_b32_e32 v40, 0
	v_mov_b32_e32 v41, 0
	v_mov_b32_e32 v42, 0
	v_mov_b32_e32 v43, 0
	v_mov_b32_e32 v44, 0
	v_mov_b32_e32 v45, 0
	v_mov_b32_e32 v46, 0
	v_mov_b32_e32 v47, 0
	v_mov_b32_e32 v48, 0
	v_mov_b32_e32 v49, 0
	v_mov_b32_e32 v50, 0
	v_mov_b32_e32 v51, 0
	v_mov_b32_e32 v52, 0
	v_mov_b32_e32 v53, 0
	v_mov_b32_e32 v54, 0
	v_mov_b32_e32 v55, 0
	v_mov_b32_e32 v8, 0
	v_mov_b32_e32 v9, 0
	v_mov_b32_e32 v10, 0
	v_mov_b32_e32 v11, 0
	v_mov_b32_e32 v12, 0
	v_mov_b32_e32 v13, 0
	v_mov_b32_e32 v14, 0
	v_mov_b32_e32 v15, 0
	v_mov_b32_e32 v16, 0
	v_mov_b32_e32 v17, 0
	v_mov_b32_e32 v18, 0
	v_mov_b32_e32 v19, 0
	v_mov_b32_e32 v20, 0
	v_mov_b32_e32 v21, 0
	v_mov_b32_e32 v22, 0
	v_mov_b32_e32 v23, 0
	v_mov_b32_e32 v164, 0
	v_mov_b32_e32 v165, 0
	v_mov_b32_e32 v166, 0
	v_mov_b32_e32 v167, 0
	v_mov_b32_e32 v172, 0
	v_mov_b32_e32 v173, 0
	v_mov_b32_e32 v174, 0
	v_mov_b32_e32 v175, 0
	v_mov_b32_e32 v176, 0
	v_mov_b32_e32 v177, 0
	v_mov_b32_e32 v178, 0
	v_mov_b32_e32 v179, 0
	v_mov_b32_e32 v180, 0
	v_mov_b32_e32 v181, 0
	v_mov_b32_e32 v182, 0
	v_mov_b32_e32 v183, 0
	v_mov_b32_e32 v170, 0
	v_mov_b32_e32 v171, 0
	v_mov_b32_e32 v201, 0
	v_mov_b32_e32 v200, 0
	s_waitcnt lgkmcnt(0)
	s_cmp_eq_u32 s24, 0
	s_cbranch_scc1 .Ldf_p_near
	v_add_f32_e32 v88, v88, v210
	v_add_f32_e32 v89, v89, v210
	v_add_f32_e32 v90, v90, v210
	v_add_f32_e32 v91, v91, v210
	v_add_f32_e32 v92, v92, v210
	v_add_f32_e32 v93, v93, v210
	v_add_f32_e32 v94, v94, v210
	v_add_f32_e32 v95, v95, v210
	v_add_f32_e32 v96, v96, v210
	v_add_f32_e32 v97, v97, v210
	v_add_f32_e32 v98, v98, v210
	v_add_f32_e32 v99, v99, v210
	v_add_f32_e32 v100, v100, v210
	v_add_f32_e32 v101, v101, v210
	v_add_f32_e32 v102, v102, v210
	v_add_f32_e32 v103, v103, v210
	v_add_f32_e32 v104, v104, v210
	v_add_f32_e32 v105, v105, v210
	v_add_f32_e32 v106, v106, v210
	v_add_f32_e32 v107, v107, v210
	v_add_f32_e32 v108, v108, v210
	v_add_f32_e32 v109, v109, v210
	v_add_f32_e32 v110, v110, v210
	v_add_f32_e32 v111, v111, v210
	v_add_f32_e32 v112, v112, v210
	v_add_f32_e32 v113, v113, v210
	v_add_f32_e32 v114, v114, v210
	v_add_f32_e32 v115, v115, v210
	v_add_f32_e32 v116, v116, v210
	v_add_f32_e32 v117, v117, v210
	v_add_f32_e32 v118, v118, v210
	v_add_f32_e32 v119, v119, v210
	s_branch .Ldf_p_biased
; #define LDS_BARRIER() asm volatile("s_waitcnt lgkmcnt(0)\n\ts_barrier" ::: "memory")
; template <int MODE>
; DI void attn_item(const Params& p, int layer, int bh, int qb, char* lds) {
;     ...
;         if (MODE != 0 && !far) {
; #pragma unroll
;           for (int sub = 0; sub < 2; ++sub)
; #pragma unroll
;             for (int r = 0; r < 16; ++r) s[sub][r] += brow[32 * sub + (r & 3) + 8 * (r >> 2)];
;         }
;         const bool first = (MODE != 2) && (t == 0) && (mp == 0);
;         auto rebase = [&]() {
;           float mx = fmaxf(fmaxf(s[0][0], s[0][1]), s[0][2]);
; #pragma unroll
;           for (int r = 3; r < 15; r += 2) mx = fmaxf(fmaxf(mx, s[0][r]), s[0][r + 1]);
;           mx = fmaxf(mx, s[0][15]);
; #pragma unroll
;           for (int r = 0; r < 16; r += 2) mx = fmaxf(fmaxf(mx, s[1][r]), s[1][r + 1]);
;           const float rm = xchg_max(mx);
;           float delta = first ? rm : fmaxf(rm, 0.f);
;           if (delta < -1e29f) delta = 0.f;
;           m += delta;
;           const float alpha = __builtin_amdgcn_exp2f(-delta);
; #pragma unroll
;           for (int mq = 0; mq < NMAP; ++mq) {
;             l[mq] *= alpha;
; #pragma unroll
;             for (int r = 0; r < 16; ++r) { O[mq][0][r] *= alpha; O[mq][1][r] *= alpha; }
;           }
; #pragma unroll
;           for (int r = 0; r < 16; ++r) { s[0][r] -= delta; s[1][r] -= delta; }
;           set_c0(cb - m);
;         };
;     ...
;   __syncthreads();
;   gload(kt0, rkA, rvA); lstore(0, rkA, rvA);
;   if (nt > 1) gload(kt0 + 1, rkB, rvB);
;   LDS_BARRIER();
;   for (int t = 0; t < nt; t += 2) {
;     if (t + 2 < nt) gload(kt0 + t + 2, rkA, rvA);
;     compute(t, 0);
;     if (t + 1 < nt) lstore(1, rkB, rvB);
;     LDS_BARRIER();
.Ldf_p_near:
	s_nop 11
	s_mov_b32 s5, 0
	v_add_u32_e32 v196, s5, v209
	ds_read2_b32 v[222:223], v196 offset0:0 offset1:1
	ds_read2_b32 v[224:225], v196 offset0:2 offset1:3
	ds_read2_b32 v[226:227], v196 offset0:8 offset1:9
	ds_read2_b32 v[228:229], v196 offset0:10 offset1:11
	ds_read2_b32 v[230:231], v196 offset0:16 offset1:17
	ds_read2_b32 v[232:233], v196 offset0:18 offset1:19
	ds_read2_b32 v[234:235], v196 offset0:24 offset1:25
	ds_read2_b32 v[236:237], v196 offset0:26 offset1:27
	s_waitcnt lgkmcnt(0)
	v_add_f32_e32 v88, v88, v222
	v_add_f32_e32 v89, v89, v223
	v_add_f32_e32 v90, v90, v224
	v_add_f32_e32 v91, v91, v225
	v_add_f32_e32 v92, v92, v226
	v_add_f32_e32 v93, v93, v227
	v_add_f32_e32 v94, v94, v228
	v_add_f32_e32 v95, v95, v229
	v_add_f32_e32 v96, v96, v230
	v_add_f32_e32 v97, v97, v231
	v_add_f32_e32 v98, v98, v232
	v_add_f32_e32 v99, v99, v233
	v_add_f32_e32 v100, v100, v234
	v_add_f32_e32 v101, v101, v235
	v_add_f32_e32 v102, v102, v236
	v_add_f32_e32 v103, v103, v237
	ds_read2_b32 v[222:223], v196 offset0:32 offset1:33
	ds_read2_b32 v[224:225], v196 offset0:34 offset1:35
	ds_read2_b32 v[226:227], v196 offset0:40 offset1:41
	ds_read2_b32 v[228:229], v196 offset0:42 offset1:43
	ds_read2_b32 v[230:231], v196 offset0:48 offset1:49
	ds_read2_b32 v[232:233], v196 offset0:50 offset1:51
	ds_read2_b32 v[234:235], v196 offset0:56 offset1:57
	ds_read2_b32 v[236:237], v196 offset0:58 offset1:59
	s_waitcnt lgkmcnt(0)
	v_add_f32_e32 v104, v104, v222
	v_add_f32_e32 v105, v105, v223
	v_add_f32_e32 v106, v106, v224
	v_add_f32_e32 v107, v107, v225
	v_add_f32_e32 v108, v108, v226
	v_add_f32_e32 v109, v109, v227
	v_add_f32_e32 v110, v110, v228
	v_add_f32_e32 v111, v111, v229
	v_add_f32_e32 v112, v112, v230
	v_add_f32_e32 v113, v113, v231
	v_add_f32_e32 v114, v114, v232
	v_add_f32_e32 v115, v115, v233
	v_add_f32_e32 v116, v116, v234
	v_add_f32_e32 v117, v117, v235
	v_add_f32_e32 v118, v118, v236
	v_add_f32_e32 v119, v119, v237
.Ldf_p_biased:
	v_max_f32_e32 v196, v88, v89
	v_max3_f32 v196, v196, v90, v91
	v_max3_f32 v196, v196, v92, v93
	v_max3_f32 v196, v196, v94, v95
	v_max3_f32 v196, v196, v96, v97
	v_max3_f32 v196, v196, v98, v99
	v_max3_f32 v196, v196, v100, v101
	v_max3_f32 v196, v196, v102, v103
	v_max3_f32 v196, v196, v104, v105
	v_max3_f32 v196, v196, v106, v107
	v_max3_f32 v196, v196, v108, v109
	v_max3_f32 v196, v196, v110, v111
	v_max3_f32 v196, v196, v112, v113
	v_max3_f32 v196, v196, v114, v115
	v_max3_f32 v196, v196, v116, v117
	v_max3_f32 v196, v196, v118, v119
	v_mov_b32_e32 v197, v196
	s_nop 1
	v_permlane32_swap_b32_e32 v196, v197
	v_max_f32_e32 v196, v196, v197
	s_mov_b32 s5, 0xefa18f08
	v_cmp_ngt_f32_e32 vcc, s5, v196
	s_nop 1
	v_cndmask_b32_e32 v200, 0, v196, vcc
	v_sub_f32_e32 v88, v88, v200
	v_sub_f32_e32 v89, v89, v200
	v_sub_f32_e32 v90, v90, v200
	v_sub_f32_e32 v91, v91, v200
	v_sub_f32_e32 v92, v92, v200
	v_sub_f32_e32 v93, v93, v200
	v_sub_f32_e32 v94, v94, v200
	v_sub_f32_e32 v95, v95, v200
	v_sub_f32_e32 v96, v96, v200
	v_sub_f32_e32 v97, v97, v200
	v_sub_f32_e32 v98, v98, v200
	v_sub_f32_e32 v99, v99, v200
	v_sub_f32_e32 v100, v100, v200
	v_sub_f32_e32 v101, v101, v200
	v_sub_f32_e32 v102, v102, v200
	v_sub_f32_e32 v103, v103, v200
	v_sub_f32_e32 v104, v104, v200
	v_sub_f32_e32 v105, v105, v200
	v_sub_f32_e32 v106, v106, v200
	v_sub_f32_e32 v107, v107, v200
	v_sub_f32_e32 v108, v108, v200
	v_sub_f32_e32 v109, v109, v200
	v_sub_f32_e32 v110, v110, v200
	v_sub_f32_e32 v111, v111, v200
	v_sub_f32_e32 v112, v112, v200
	v_sub_f32_e32 v113, v113, v200
	v_sub_f32_e32 v114, v114, v200
	v_sub_f32_e32 v115, v115, v200
	v_sub_f32_e32 v116, v116, v200
	v_sub_f32_e32 v117, v117, v200
	v_sub_f32_e32 v118, v118, v200
	v_sub_f32_e32 v119, v119, v200
	s_cmp_eq_u32 s24, 0
	s_cbranch_scc1 .Ldf_p_c0n
	v_sub_f32_e32 v198, v210, v200
	v_bfe_u32 v197, v198, 16, 1
	v_add3_u32 v196, v198, v197, s45
	v_lshrrev_b32_e32 v197, 16, v196
	v_and_b32_e32 v196, 0xffff0000, v196
	v_sub_f32_e32 v196, v198, v196
	v_bfe_u32 v198, v196, 16, 1
	v_add3_u32 v196, v196, v198, s45
	v_and_or_b32 v196, v196, s92, v197
	v_cndmask_b32_e64 v226, 0, v196, s[6:7]
	v_mov_b32_e32 v196, 0x3f803f80
	v_cndmask_b32_e64 v222, 0, v196, s[6:7]
	v_mov_b32_e32 v223, 0
	v_mov_b32_e32 v227, 0
	v_mov_b32_e32 v224, 0
	v_mov_b32_e32 v228, 0
	v_mov_b32_e32 v225, 0
	v_mov_b32_e32 v229, 0
	s_nop 1
	v_mfma_f32_32x32x16_bf16 v[72:87], v[222:225], v[226:229], 0
	s_branch .Ldf_p_c0d
.Ldf_p_c0n:
	v_sub_f32_e32 v198, 0, v200
	v_bfe_u32 v197, v198, 16, 1
	v_add3_u32 v196, v198, v197, s45
	v_lshrrev_b32_e32 v197, 16, v196
	v_and_b32_e32 v196, 0xffff0000, v196
	v_sub_f32_e32 v196, v198, v196
	v_bfe_u32 v198, v196, 16, 1
	v_add3_u32 v196, v196, v198, s45
	v_and_or_b32 v196, v196, s92, v197
	v_cndmask_b32_e64 v226, 0, v196, s[6:7]
	v_mov_b32_e32 v196, 0x3f803f80
	v_cndmask_b32_e64 v222, 0, v196, s[6:7]
	v_mov_b32_e32 v223, 0
	v_mov_b32_e32 v227, 0
	v_mov_b32_e32 v224, 0
	v_mov_b32_e32 v228, 0
	v_mov_b32_e32 v225, 0
	v_mov_b32_e32 v229, 0
	s_nop 1
	v_mfma_f32_32x32x16_bf16 v[72:87], v[222:225], v[226:229], 0
.Ldf_p_c0d:
	s_nop 11
	s_mov_b32 s62, 0
.Ldf_loop:
	s_waitcnt vmcnt(0)
	ds_write_b128 v206, v[238:241] offset:45056
	ds_write_b128 v207, v[242:245] offset:32768
	buffer_load_dwordx4 v[246:249], v208, s[8:11], s93 offen
	buffer_load_dwordx4 v[250:253], v208, s[12:15], s28 offen
	s_add_u32 s93, s93, 0x2000
	s_add_u32 s28, s28, 0x2000
	s_cmp_ge_u32 s62, s24
	s_cbranch_scc0 .Ldf_s1_0
	s_cmp_lt_u32 s62, s25
	s_cbranch_scc1 .Ldf_fixa_0
; template <int MODE>
; DI void attn_item(const Params& p, int layer, int bh, int qb, char* lds) {
;     ...
;         if (MODE != 0 && !far) {
; #pragma unroll
;           for (int sub = 0; sub < 2; ++sub)
; #pragma unroll
;             for (int r = 0; r < 16; ++r) s[sub][r] += brow[32 * sub + (r & 3) + 8 * (r >> 2)];
;         }
;         const bool first = (MODE != 2) && (t == 0) && (mp == 0);
;         auto rebase = [&]() {
;           float mx = fmaxf(fmaxf(s[0][0], s[0][1]), s[0][2]);
; #pragma unroll
;           for (int r = 3; r < 15; r += 2) mx = fmaxf(fmaxf(mx, s[0][r]), s[0][r + 1]);
;           mx = fmaxf(mx, s[0][15]);
; #pragma unroll
;           for (int r = 0; r < 16; r += 2) mx = fmaxf(fmaxf(mx, s[1][r]), s[1][r + 1]);
;           const float rm = xchg_max(mx);
;           float delta = first ? rm : fmaxf(rm, 0.f);
;           if (delta < -1e29f) delta = 0.f;
;           m += delta;
;           const float alpha = __builtin_amdgcn_exp2f(-delta);
; #pragma unroll
;           for (int mq = 0; mq < NMAP; ++mq) {
;             l[mq] *= alpha;
; #pragma unroll
;             for (int r = 0; r < 16; ++r) { O[mq][0][r] *= alpha; O[mq][1][r] *= alpha; }
;           }
; #pragma unroll
;           for (int r = 0; r < 16; ++r) { s[0][r] -= delta; s[1][r] -= delta; }
;           set_c0(cb - m);
;         };
;         float ps;
;         auto smpass = [&]() {
;           ps = 0.f;
; #pragma unroll
;           for (int sub = 0; sub < 2; ++sub)
; #pragma unroll
;             for (int ks = 0; ks < 2; ++ks)
; #pragma unroll
;               for (int i = 0; i < 4; ++i) {
;                 const float p0 = __builtin_amdgcn_exp2f(s[sub][8 * ks + 2 * i]), p1 = __builtin_amdgcn_exp2f(s[sub][8 * ks + 2 * i + 1]);
;                 ps += p0 + p1; pk[mp][sub][ks][i] = pk2(p0, p1);
;               }
;         };
;         if (first) rebase();
;         smpass();
;     ...
;         __builtin_amdgcn_s_setprio(1);
; #pragma unroll
;         for (int ks = 0; ks < 2; ++ks) {
; #pragma unroll
;           for (int dt = 0; dt < 2; ++dt) {
;             s16x4 lo = vv[ks * 4 + dt * 2], hi = vv[ks * 4 + dt * 2 + 1];
;             bf16x8 vf = __builtin_shufflevector(lo, hi, 0, 1, 2, 3, 4, 5, 6, 7);
; #pragma unroll
;             for (int mp = 0; mp < NMAP; ++mp) O[mp][dt] = MFMA(vf, __builtin_bit_cast(bf16x8, pk[mp][sub][ks]), O[mp][dt]);
;           }
;         }
.Ldf_s1_0:
	ds_read_b64_tr_b16 v[222:223], v205 offset:54272
	ds_read_b64_tr_b16 v[224:225], v205 offset:55808
	ds_read_b64_tr_b16 v[226:227], v205 offset:54336
	ds_read_b64_tr_b16 v[228:229], v205 offset:55872
	ds_read_b128 v[230:233], v204 offset:2112
	v_exp_f32_e32 v6, v88
	v_exp_f32_e32 v7, v89
	v_exp_f32_e32 v186, v90
	v_exp_f32_e32 v187, v91
	s_waitcnt lgkmcnt(3)
	v_mfma_f32_32x32x16_bf16 v[40:55], v[222:225], v[164:167], v[40:55]
	ds_read_b64_tr_b16 v[234:235], v205 offset:57344
	ds_read_b64_tr_b16 v[236:237], v205 offset:58880
	v_add_f32_e32 v192, v6, v7
	s_waitcnt lgkmcnt(3)
	v_mfma_f32_32x32x16_bf16 v[8:23], v[226:229], v[164:167], v[8:23]
	ds_read_b64_tr_b16 v[222:223], v205 offset:57408
	ds_read_b64_tr_b16 v[224:225], v205 offset:58944
	v_cvt_pk_bf16_f32 v164, v6, v7
	v_add_f32_e32 v192, v192, v186
	v_add_f32_e32 v192, v192, v187
	v_cvt_pk_bf16_f32 v165, v186, v187
	v_exp_f32_e32 v188, v92
	v_exp_f32_e32 v189, v93
	v_exp_f32_e32 v190, v94
	s_waitcnt lgkmcnt(4)
	v_mfma_f32_32x32x16_bf16 v[132:147], v[230:233], v[124:127], v[72:87]
	ds_read_b128 v[226:229], v204 offset:2144
	v_exp_f32_e32 v191, v95
	v_add_f32_e32 v192, v192, v188
	v_add_f32_e32 v192, v192, v189
	v_cvt_pk_bf16_f32 v166, v188, v189
	v_add_f32_e32 v192, v192, v190
	v_add_f32_e32 v192, v192, v191
	v_cvt_pk_bf16_f32 v167, v190, v191
	s_waitcnt lgkmcnt(3)
	v_mfma_f32_32x32x16_bf16 v[40:55], v[234:237], v[172:175], v[40:55]
	ds_read_b64_tr_b16 v[230:231], v205 offset:60416
	ds_read_b64_tr_b16 v[232:233], v205 offset:61952
	v_exp_f32_e32 v6, v96
	v_exp_f32_e32 v7, v97
	v_exp_f32_e32 v186, v98
	v_exp_f32_e32 v187, v99
	v_add_f32_e32 v193, v6, v7
	s_waitcnt lgkmcnt(3)
	v_mfma_f32_32x32x16_bf16 v[8:23], v[222:225], v[172:175], v[8:23]
	ds_read_b64_tr_b16 v[234:235], v205 offset:60480
	ds_read_b64_tr_b16 v[236:237], v205 offset:62016
	v_cvt_pk_bf16_f32 v172, v6, v7
	v_add_f32_e32 v193, v193, v186
	v_add_f32_e32 v193, v193, v187
	v_cvt_pk_bf16_f32 v173, v186, v187
	v_exp_f32_e32 v188, v100
	v_exp_f32_e32 v189, v101
	v_exp_f32_e32 v190, v102
	s_waitcnt lgkmcnt(4)
	v_mfma_f32_32x32x16_bf16 v[132:147], v[226:229], v[128:131], v[132:147]
	ds_read_b128 v[222:225], v204 offset:6720
	v_exp_f32_e32 v191, v103
	v_add_f32_e32 v193, v193, v188
	v_add_f32_e32 v193, v193, v189
	v_cvt_pk_bf16_f32 v174, v188, v189
	v_add_f32_e32 v193, v193, v190
	v_add_f32_e32 v193, v193, v191
	v_cvt_pk_bf16_f32 v175, v190, v191
	s_waitcnt lgkmcnt(3)
	v_mfma_f32_32x32x16_bf16 v[40:55], v[230:233], v[176:179], v[40:55]
	ds_read_b64_tr_b16 v[226:227], v205 offset:63488
	ds_read_b64_tr_b16 v[228:229], v205 offset:65024
	v_exp_f32_e32 v6, v104
	v_exp_f32_e32 v7, v105
	v_exp_f32_e32 v186, v106
	v_exp_f32_e32 v187, v107
	v_add_f32_e32 v194, v6, v7
	s_waitcnt lgkmcnt(3)
	v_mfma_f32_32x32x16_bf16 v[8:23], v[234:237], v[176:179], v[8:23]
	ds_read_b64_tr_b16 v[230:231], v205 offset:63552
	ds_read_b64_tr_b16 v[232:233], v205 offset:65088
	v_cvt_pk_bf16_f32 v176, v6, v7
	v_add_f32_e32 v194, v194, v186
	v_add_f32_e32 v194, v194, v187
	v_cvt_pk_bf16_f32 v177, v186, v187
	v_exp_f32_e32 v188, v108
	v_exp_f32_e32 v189, v109
	v_exp_f32_e32 v190, v110
	s_waitcnt lgkmcnt(4)
	v_mfma_f32_32x32x16_bf16 v[148:163], v[222:225], v[124:127], v[72:87]
	ds_read_b128 v[234:237], v204 offset:6752
	v_exp_f32_e32 v191, v111
	v_add_f32_e32 v194, v194, v188
	v_add_f32_e32 v194, v194, v189
	v_cvt_pk_bf16_f32 v178, v188, v189
	v_add_f32_e32 v194, v194, v190
	v_add_f32_e32 v194, v194, v191
	v_cvt_pk_bf16_f32 v179, v190, v191
	s_waitcnt lgkmcnt(3)
	v_mfma_f32_32x32x16_bf16 v[40:55], v[226:229], v[180:183], v[40:55]
	v_exp_f32_e32 v6, v112
	v_exp_f32_e32 v7, v113
	v_exp_f32_e32 v186, v114
	v_exp_f32_e32 v187, v115
	v_add_f32_e32 v195, v6, v7
	s_waitcnt lgkmcnt(1)
	v_mfma_f32_32x32x16_bf16 v[8:23], v[230:233], v[180:183], v[8:23]
	v_cvt_pk_bf16_f32 v180, v6, v7
	v_add_f32_e32 v195, v195, v186
	v_add_f32_e32 v195, v195, v187
	v_cvt_pk_bf16_f32 v181, v186, v187
	v_exp_f32_e32 v188, v116
	v_exp_f32_e32 v189, v117
	v_exp_f32_e32 v190, v118
	s_waitcnt lgkmcnt(0)
	v_mfma_f32_32x32x16_bf16 v[148:163], v[234:237], v[128:131], v[148:163]
	v_exp_f32_e32 v191, v119
	v_add_f32_e32 v195, v195, v188
	v_add_f32_e32 v195, v195, v189
	v_cvt_pk_bf16_f32 v182, v188, v189
	v_add_f32_e32 v195, v195, v190
	v_add_f32_e32 v195, v195, v191
	v_cvt_pk_bf16_f32 v183, v190, v191
	v_add_f32_e32 v192, v192, v193
	v_add_f32_e32 v194, v194, v195
	v_add_f32_e32 v192, v192, v194
	v_add_f32_e32 v170, v170, v192
	v_max_f32_e32 v201, v201, v192
	s_add_u32 s4, s62, 1
	s_cmp_eq_u32 s4, s24
	s_cbranch_scc1 .Ldf_c0n_0
	s_cmp_eq_u32 s4, s25
	s_cbranch_scc1 .Ldf_c0r_0
.Ldf_c0d_0:
	s_cmp_ge_u32 s62, s24
	s_cbranch_scc0 .Ldf_s2_0
	s_cmp_lt_u32 s62, s25
	s_cbranch_scc1 .Ldf_fixb_0
; #define MFMA(a, b, c) __builtin_amdgcn_mfma_f32_32x32x16_bf16((a), (b), (c), 0, 0, 0)
; DI unsigned pk2(float lo, float hi) { f32x2 v = {lo, hi}; b16x2 r = __builtin_convertvector(v, b16x2); return __builtin_bit_cast(unsigned, r); }
; #define LDS_BARRIER() asm volatile("s_waitcnt lgkmcnt(0)\n\ts_barrier" ::: "memory")
; template <int MODE>
; DI void attn_item(const Params& p, int layer, int bh, int qb, char* lds) {
;     ...
;         auto smpass = [&]() {
;           ps = 0.f;
; #pragma unroll
;           for (int sub = 0; sub < 2; ++sub)
; #pragma unroll
;             for (int ks = 0; ks < 2; ++ks)
; #pragma unroll
;               for (int i = 0; i < 4; ++i) {
;                 const float p0 = __builtin_amdgcn_exp2f(s[sub][8 * ks + 2 * i]), p1 = __builtin_amdgcn_exp2f(s[sub][8 * ks + 2 * i + 1]);
;                 ps += p0 + p1; pk[mp][sub][ks][i] = pk2(p0, p1);
;               }
;         };
;         if (first) rebase();
;         smpass();
;         if (!first && __any(!(ps <= PSLIM))) { rebase(); smpass(); }
;         l[mp] += ps;
;         __builtin_amdgcn_sched_barrier(0);
;       }
; #pragma unroll
;       for (int sub = 0; sub < 2; ++sub) {
;         s16x4 vv[8];
;         if (NMAP == 1) {
; #pragma unroll
;           for (int i = 0; i < 8; ++i) vv[i] = vpre[sub * 8 + i];
;         } else {
;           if (sub == 0) trread8<0>(vaddr, vv); else trread8<32 * VSTR>(vaddr, vv);
;         }
;         __builtin_amdgcn_s_setprio(1);
; #pragma unroll
;         for (int ks = 0; ks < 2; ++ks) {
; #pragma unroll
;           for (int dt = 0; dt < 2; ++dt) {
;             s16x4 lo = vv[ks * 4 + dt * 2], hi = vv[ks * 4 + dt * 2 + 1];
;             bf16x8 vf = __builtin_shufflevector(lo, hi, 0, 1, 2, 3, 4, 5, 6, 7);
; #pragma unroll
;             for (int mp = 0; mp < NMAP; ++mp) O[mp][dt] = MFMA(vf, __builtin_bit_cast(bf16x8, pk[mp][sub][ks]), O[mp][dt]);
;           }
;         }
;         __builtin_amdgcn_s_setprio(0);
;         __builtin_amdgcn_sched_barrier(0);
;       }
;     ...
;   for (int t = 0; t < nt; t += 2) {
;     if (t + 2 < nt) gload(kt0 + t + 2, rkA, rvA);
;     compute(t, 0);
;     if (t + 1 < nt) lstore(1, rkB, rvB);
;     LDS_BARRIER();
;     if (t + 1 >= nt) break;
;     if (t + 3 < nt) gload(kt0 + t + 3, rkB, rvB);
;     compute(t + 1, 1);
;     if (t + 2 < nt) lstore(0, rkA, rvA);
;     LDS_BARRIER();
.Ldf_s2_0:
	ds_read_b64_tr_b16 v[222:223], v205 offset:11264
	ds_read_b64_tr_b16 v[224:225], v205 offset:12800
	ds_read_b64_tr_b16 v[226:227], v205 offset:11328
	ds_read_b64_tr_b16 v[228:229], v205 offset:12864
	ds_read_b128 v[230:233], v204 offset:23552
	v_exp_f32_e32 v6, v132
	v_exp_f32_e32 v7, v133
	v_exp_f32_e32 v186, v134
	v_exp_f32_e32 v187, v135
	s_waitcnt lgkmcnt(3)
	v_mfma_f32_32x32x16_bf16 v[56:71], v[222:225], v[164:167], v[56:71]
	ds_read_b64_tr_b16 v[234:235], v205 offset:14336
	ds_read_b64_tr_b16 v[236:237], v205 offset:15872
	v_add_f32_e32 v192, v6, v7
	s_waitcnt lgkmcnt(3)
	v_mfma_f32_32x32x16_bf16 v[24:39], v[226:229], v[164:167], v[24:39]
	ds_read_b64_tr_b16 v[222:223], v205 offset:14400
	ds_read_b64_tr_b16 v[224:225], v205 offset:15936
	v_cvt_pk_bf16_f32 v164, v6, v7
	v_add_f32_e32 v192, v192, v186
	v_add_f32_e32 v192, v192, v187
	v_cvt_pk_bf16_f32 v165, v186, v187
	v_exp_f32_e32 v188, v136
	v_exp_f32_e32 v189, v137
	v_exp_f32_e32 v190, v138
	s_waitcnt lgkmcnt(4)
	v_mfma_f32_32x32x16_bf16 v[88:103], v[230:233], v[0:3], v[72:87]
	ds_read_b128 v[226:229], v204 offset:23584
	v_exp_f32_e32 v191, v139
	v_add_f32_e32 v192, v192, v188
	v_add_f32_e32 v192, v192, v189
	v_cvt_pk_bf16_f32 v166, v188, v189
	v_add_f32_e32 v192, v192, v190
	v_add_f32_e32 v192, v192, v191
	v_cvt_pk_bf16_f32 v167, v190, v191
	s_waitcnt lgkmcnt(3)
	v_mfma_f32_32x32x16_bf16 v[56:71], v[234:237], v[172:175], v[56:71]
	ds_read_b64_tr_b16 v[230:231], v205 offset:17408
	ds_read_b64_tr_b16 v[232:233], v205 offset:18944
	v_exp_f32_e32 v6, v140
	v_exp_f32_e32 v7, v141
	v_exp_f32_e32 v186, v142
	v_exp_f32_e32 v187, v143
	v_add_f32_e32 v193, v6, v7
	s_waitcnt lgkmcnt(3)
	v_mfma_f32_32x32x16_bf16 v[24:39], v[222:225], v[172:175], v[24:39]
	ds_read_b64_tr_b16 v[234:235], v205 offset:17472
	ds_read_b64_tr_b16 v[236:237], v205 offset:19008
	v_cvt_pk_bf16_f32 v172, v6, v7
	v_add_f32_e32 v193, v193, v186
	v_add_f32_e32 v193, v193, v187
	v_cvt_pk_bf16_f32 v173, v186, v187
	v_exp_f32_e32 v188, v144
	v_exp_f32_e32 v189, v145
	v_exp_f32_e32 v190, v146
	s_waitcnt lgkmcnt(4)
	v_mfma_f32_32x32x16_bf16 v[88:103], v[226:229], v[120:123], v[88:103]
	ds_read_b128 v[222:225], v204 offset:28160
	v_exp_f32_e32 v191, v147
	v_add_f32_e32 v193, v193, v188
	v_add_f32_e32 v193, v193, v189
	v_cvt_pk_bf16_f32 v174, v188, v189
	v_add_f32_e32 v193, v193, v190
	v_add_f32_e32 v193, v193, v191
	v_cvt_pk_bf16_f32 v175, v190, v191
	s_waitcnt lgkmcnt(3)
	v_mfma_f32_32x32x16_bf16 v[56:71], v[230:233], v[176:179], v[56:71]
	ds_read_b64_tr_b16 v[226:227], v205 offset:20480
	ds_read_b64_tr_b16 v[228:229], v205 offset:22016
	v_exp_f32_e32 v6, v148
	v_exp_f32_e32 v7, v149
	v_exp_f32_e32 v186, v150
	v_exp_f32_e32 v187, v151
	v_add_f32_e32 v194, v6, v7
	s_waitcnt lgkmcnt(3)
	v_mfma_f32_32x32x16_bf16 v[24:39], v[234:237], v[176:179], v[24:39]
	ds_read_b64_tr_b16 v[230:231], v205 offset:20544
	ds_read_b64_tr_b16 v[232:233], v205 offset:22080
	v_cvt_pk_bf16_f32 v176, v6, v7
	v_add_f32_e32 v194, v194, v186
	v_add_f32_e32 v194, v194, v187
	v_cvt_pk_bf16_f32 v177, v186, v187
	v_exp_f32_e32 v188, v152
	v_exp_f32_e32 v189, v153
	v_exp_f32_e32 v190, v154
	s_waitcnt lgkmcnt(4)
	v_mfma_f32_32x32x16_bf16 v[104:119], v[222:225], v[0:3], v[72:87]
	ds_read_b128 v[234:237], v204 offset:28192
	v_exp_f32_e32 v191, v155
	v_add_f32_e32 v194, v194, v188
	v_add_f32_e32 v194, v194, v189
	v_cvt_pk_bf16_f32 v178, v188, v189
	v_add_f32_e32 v194, v194, v190
	v_add_f32_e32 v194, v194, v191
	v_cvt_pk_bf16_f32 v179, v190, v191
	s_waitcnt lgkmcnt(3)
	v_mfma_f32_32x32x16_bf16 v[56:71], v[226:229], v[180:183], v[56:71]
	v_exp_f32_e32 v6, v156
	v_exp_f32_e32 v7, v157
	v_exp_f32_e32 v186, v158
	v_exp_f32_e32 v187, v159
	v_add_f32_e32 v195, v6, v7
	s_waitcnt lgkmcnt(1)
	v_mfma_f32_32x32x16_bf16 v[24:39], v[230:233], v[180:183], v[24:39]
	v_cvt_pk_bf16_f32 v180, v6, v7
	v_add_f32_e32 v195, v195, v186
	v_add_f32_e32 v195, v195, v187
	v_cvt_pk_bf16_f32 v181, v186, v187
	v_exp_f32_e32 v188, v160
	v_exp_f32_e32 v189, v161
	v_exp_f32_e32 v190, v162
	s_waitcnt lgkmcnt(0)
	v_mfma_f32_32x32x16_bf16 v[104:119], v[234:237], v[120:123], v[104:119]
	v_exp_f32_e32 v191, v163
	v_add_f32_e32 v195, v195, v188
	v_add_f32_e32 v195, v195, v189
	v_cvt_pk_bf16_f32 v182, v188, v189
	v_add_f32_e32 v195, v195, v190
	v_add_f32_e32 v195, v195, v191
	v_cvt_pk_bf16_f32 v183, v190, v191
	v_add_f32_e32 v192, v192, v193
	v_add_f32_e32 v194, v194, v195
	v_add_f32_e32 v192, v192, v194
	v_add_f32_e32 v171, v171, v192
	v_max_f32_e32 v201, v201, v192
	s_add_u32 s62, s62, 1
	s_waitcnt lgkmcnt(0)
	s_barrier
	s_waitcnt vmcnt(0)
	ds_write_b128 v206, v[246:249] offset:2048
	ds_write_b128 v207, v[250:253] offset:54272
	buffer_load_dwordx4 v[238:241], v208, s[8:11], s93 offen
	buffer_load_dwordx4 v[242:245], v208, s[12:15], s28 offen
	s_add_u32 s93, s93, 0x2000
	s_add_u32 s28, s28, 0x2000
	s_cmp_ge_u32 s62, s24
	s_cbranch_scc0 .Ldf_s1_1
	s_cmp_lt_u32 s62, s25
	s_cbranch_scc1 .Ldf_fixa_1
; #define MFMA(a, b, c) __builtin_amdgcn_mfma_f32_32x32x16_bf16((a), (b), (c), 0, 0, 0)
; DI unsigned pk2(float lo, float hi) { f32x2 v = {lo, hi}; b16x2 r = __builtin_convertvector(v, b16x2); return __builtin_bit_cast(unsigned, r); }
; #define LDS_BARRIER() asm volatile("s_waitcnt lgkmcnt(0)\n\ts_barrier" ::: "memory")
; template <int MODE>
; DI void attn_item(const Params& p, int layer, int bh, int qb, char* lds) {
;     ...
;         auto smpass = [&]() {
;           ps = 0.f;
; #pragma unroll
;           for (int sub = 0; sub < 2; ++sub)
; #pragma unroll
;             for (int ks = 0; ks < 2; ++ks)
; #pragma unroll
;               for (int i = 0; i < 4; ++i) {
;                 const float p0 = __builtin_amdgcn_exp2f(s[sub][8 * ks + 2 * i]), p1 = __builtin_amdgcn_exp2f(s[sub][8 * ks + 2 * i + 1]);
;                 ps += p0 + p1; pk[mp][sub][ks][i] = pk2(p0, p1);
;               }
;         };
;         if (first) rebase();
;         smpass();
;         if (!first && __any(!(ps <= PSLIM))) { rebase(); smpass(); }
;         l[mp] += ps;
;         __builtin_amdgcn_sched_barrier(0);
;       }
; #pragma unroll
;       for (int sub = 0; sub < 2; ++sub) {
;         s16x4 vv[8];
;         if (NMAP == 1) {
; #pragma unroll
;           for (int i = 0; i < 8; ++i) vv[i] = vpre[sub * 8 + i];
;         } else {
;           if (sub == 0) trread8<0>(vaddr, vv); else trread8<32 * VSTR>(vaddr, vv);
;         }
;         __builtin_amdgcn_s_setprio(1);
; #pragma unroll
;         for (int ks = 0; ks < 2; ++ks) {
; #pragma unroll
;           for (int dt = 0; dt < 2; ++dt) {
;             s16x4 lo = vv[ks * 4 + dt * 2], hi = vv[ks * 4 + dt * 2 + 1];
;             bf16x8 vf = __builtin_shufflevector(lo, hi, 0, 1, 2, 3, 4, 5, 6, 7);
; #pragma unroll
;             for (int mp = 0; mp < NMAP; ++mp) O[mp][dt] = MFMA(vf, __builtin_bit_cast(bf16x8, pk[mp][sub][ks]), O[mp][dt]);
;           }
;         }
;         __builtin_amdgcn_s_setprio(0);
;         __builtin_amdgcn_sched_barrier(0);
;       }
;     ...
;   for (int t = 0; t < nt; t += 2) {
;     if (t + 2 < nt) gload(kt0 + t + 2, rkA, rvA);
;     compute(t, 0);
;     if (t + 1 < nt) lstore(1, rkB, rvB);
;     LDS_BARRIER();
.Ldf_s1_1:
	ds_read_b64_tr_b16 v[222:223], v205 offset:11264
	ds_read_b64_tr_b16 v[224:225], v205 offset:12800
	ds_read_b64_tr_b16 v[226:227], v205 offset:11328
	ds_read_b64_tr_b16 v[228:229], v205 offset:12864
	ds_read_b128 v[230:233], v204 offset:23616
	v_exp_f32_e32 v6, v88
	v_exp_f32_e32 v7, v89
	v_exp_f32_e32 v186, v90
	v_exp_f32_e32 v187, v91
	s_waitcnt lgkmcnt(3)
	v_mfma_f32_32x32x16_bf16 v[40:55], v[222:225], v[164:167], v[40:55]
	ds_read_b64_tr_b16 v[234:235], v205 offset:14336
	ds_read_b64_tr_b16 v[236:237], v205 offset:15872
	v_add_f32_e32 v192, v6, v7
	s_waitcnt lgkmcnt(3)
	v_mfma_f32_32x32x16_bf16 v[8:23], v[226:229], v[164:167], v[8:23]
	ds_read_b64_tr_b16 v[222:223], v205 offset:14400
	ds_read_b64_tr_b16 v[224:225], v205 offset:15936
	v_cvt_pk_bf16_f32 v164, v6, v7
	v_add_f32_e32 v192, v192, v186
	v_add_f32_e32 v192, v192, v187
	v_cvt_pk_bf16_f32 v165, v186, v187
	v_exp_f32_e32 v188, v92
	v_exp_f32_e32 v189, v93
	v_exp_f32_e32 v190, v94
	s_waitcnt lgkmcnt(4)
	v_mfma_f32_32x32x16_bf16 v[132:147], v[230:233], v[124:127], v[72:87]
	ds_read_b128 v[226:229], v204 offset:23648
	v_exp_f32_e32 v191, v95
	v_add_f32_e32 v192, v192, v188
	v_add_f32_e32 v192, v192, v189
	v_cvt_pk_bf16_f32 v166, v188, v189
	v_add_f32_e32 v192, v192, v190
	v_add_f32_e32 v192, v192, v191
	v_cvt_pk_bf16_f32 v167, v190, v191
	s_waitcnt lgkmcnt(3)
	v_mfma_f32_32x32x16_bf16 v[40:55], v[234:237], v[172:175], v[40:55]
	ds_read_b64_tr_b16 v[230:231], v205 offset:17408
	ds_read_b64_tr_b16 v[232:233], v205 offset:18944
	v_exp_f32_e32 v6, v96
	v_exp_f32_e32 v7, v97
	v_exp_f32_e32 v186, v98
	v_exp_f32_e32 v187, v99
	v_add_f32_e32 v193, v6, v7
	s_waitcnt lgkmcnt(3)
	v_mfma_f32_32x32x16_bf16 v[8:23], v[222:225], v[172:175], v[8:23]
	ds_read_b64_tr_b16 v[234:235], v205 offset:17472
	ds_read_b64_tr_b16 v[236:237], v205 offset:19008
	v_cvt_pk_bf16_f32 v172, v6, v7
	v_add_f32_e32 v193, v193, v186
	v_add_f32_e32 v193, v193, v187
	v_cvt_pk_bf16_f32 v173, v186, v187
	v_exp_f32_e32 v188, v100
	v_exp_f32_e32 v189, v101
	v_exp_f32_e32 v190, v102
	s_waitcnt lgkmcnt(4)
	v_mfma_f32_32x32x16_bf16 v[132:147], v[226:229], v[128:131], v[132:147]
	ds_read_b128 v[222:225], v204 offset:28224
	v_exp_f32_e32 v191, v103
	v_add_f32_e32 v193, v193, v188
	v_add_f32_e32 v193, v193, v189
	v_cvt_pk_bf16_f32 v174, v188, v189
	v_add_f32_e32 v193, v193, v190
	v_add_f32_e32 v193, v193, v191
	v_cvt_pk_bf16_f32 v175, v190, v191
	s_waitcnt lgkmcnt(3)
	v_mfma_f32_32x32x16_bf16 v[40:55], v[230:233], v[176:179], v[40:55]
	ds_read_b64_tr_b16 v[226:227], v205 offset:20480
	ds_read_b64_tr_b16 v[228:229], v205 offset:22016
	v_exp_f32_e32 v6, v104
	v_exp_f32_e32 v7, v105
	v_exp_f32_e32 v186, v106
	v_exp_f32_e32 v187, v107
	v_add_f32_e32 v194, v6, v7
	s_waitcnt lgkmcnt(3)
	v_mfma_f32_32x32x16_bf16 v[8:23], v[234:237], v[176:179], v[8:23]
	ds_read_b64_tr_b16 v[230:231], v205 offset:20544
	ds_read_b64_tr_b16 v[232:233], v205 offset:22080
	v_cvt_pk_bf16_f32 v176, v6, v7
	v_add_f32_e32 v194, v194, v186
	v_add_f32_e32 v194, v194, v187
	v_cvt_pk_bf16_f32 v177, v186, v187
	v_exp_f32_e32 v188, v108
	v_exp_f32_e32 v189, v109
	v_exp_f32_e32 v190, v110
	s_waitcnt lgkmcnt(4)
	v_mfma_f32_32x32x16_bf16 v[148:163], v[222:225], v[124:127], v[72:87]
	ds_read_b128 v[234:237], v204 offset:28256
	v_exp_f32_e32 v191, v111
	v_add_f32_e32 v194, v194, v188
	v_add_f32_e32 v194, v194, v189
	v_cvt_pk_bf16_f32 v178, v188, v189
	v_add_f32_e32 v194, v194, v190
	v_add_f32_e32 v194, v194, v191
	v_cvt_pk_bf16_f32 v179, v190, v191
	s_waitcnt lgkmcnt(3)
	v_mfma_f32_32x32x16_bf16 v[40:55], v[226:229], v[180:183], v[40:55]
	v_exp_f32_e32 v6, v112
	v_exp_f32_e32 v7, v113
	v_exp_f32_e32 v186, v114
	v_exp_f32_e32 v187, v115
	v_add_f32_e32 v195, v6, v7
	s_waitcnt lgkmcnt(1)
	v_mfma_f32_32x32x16_bf16 v[8:23], v[230:233], v[180:183], v[8:23]
	v_cvt_pk_bf16_f32 v180, v6, v7
	v_add_f32_e32 v195, v195, v186
	v_add_f32_e32 v195, v195, v187
	v_cvt_pk_bf16_f32 v181, v186, v187
	v_exp_f32_e32 v188, v116
	v_exp_f32_e32 v189, v117
	v_exp_f32_e32 v190, v118
	s_waitcnt lgkmcnt(0)
	v_mfma_f32_32x32x16_bf16 v[148:163], v[234:237], v[128:131], v[148:163]
	v_exp_f32_e32 v191, v119
	v_add_f32_e32 v195, v195, v188
	v_add_f32_e32 v195, v195, v189
	v_cvt_pk_bf16_f32 v182, v188, v189
	v_add_f32_e32 v195, v195, v190
	v_add_f32_e32 v195, v195, v191
	v_cvt_pk_bf16_f32 v183, v190, v191
	v_add_f32_e32 v192, v192, v193
	v_add_f32_e32 v194, v194, v195
	v_add_f32_e32 v192, v192, v194
	v_add_f32_e32 v170, v170, v192
	v_max_f32_e32 v201, v201, v192
	s_add_u32 s4, s62, 1
	s_cmp_eq_u32 s4, s24
	s_cbranch_scc1 .Ldf_c0n_1
	s_cmp_eq_u32 s4, s25
	s_cbranch_scc1 .Ldf_c0r_1

; #define MFMA(a, b, c) __builtin_amdgcn_mfma_f32_32x32x16_bf16((a), (b), (c), 0, 0, 0)
; DI unsigned pk2(float lo, float hi) { f32x2 v = {lo, hi}; b16x2 r = __builtin_convertvector(v, b16x2); return __builtin_bit_cast(unsigned, r); }
; #define LDS_BARRIER() asm volatile("s_waitcnt lgkmcnt(0)\n\ts_barrier" ::: "memory")
; template <int MODE>
; DI void attn_item(const Params& p, int layer, int bh, int qb, char* lds) {
;     ...
;         auto smpass = [&]() {
;           ps = 0.f;
; #pragma unroll
;           for (int sub = 0; sub < 2; ++sub)
; #pragma unroll
;             for (int ks = 0; ks < 2; ++ks)
; #pragma unroll
;               for (int i = 0; i < 4; ++i) {
;                 const float p0 = __builtin_amdgcn_exp2f(s[sub][8 * ks + 2 * i]), p1 = __builtin_amdgcn_exp2f(s[sub][8 * ks + 2 * i + 1]);
;                 ps += p0 + p1; pk[mp][sub][ks][i] = pk2(p0, p1);
;               }
;         };
;         if (first) rebase();
;         smpass();
;         if (!first && __any(!(ps <= PSLIM))) { rebase(); smpass(); }
;         l[mp] += ps;
;         __builtin_amdgcn_sched_barrier(0);
;       }
; #pragma unroll
;       for (int sub = 0; sub < 2; ++sub) {
;         s16x4 vv[8];
;         if (NMAP == 1) {
; #pragma unroll
;           for (int i = 0; i < 8; ++i) vv[i] = vpre[sub * 8 + i];
;         } else {
;           if (sub == 0) trread8<0>(vaddr, vv); else trread8<32 * VSTR>(vaddr, vv);
;         }
;         __builtin_amdgcn_s_setprio(1);
; #pragma unroll
;         for (int ks = 0; ks < 2; ++ks) {
; #pragma unroll
;           for (int dt = 0; dt < 2; ++dt) {
;             s16x4 lo = vv[ks * 4 + dt * 2], hi = vv[ks * 4 + dt * 2 + 1];
;             bf16x8 vf = __builtin_shufflevector(lo, hi, 0, 1, 2, 3, 4, 5, 6, 7);
; #pragma unroll
;             for (int mp = 0; mp < NMAP; ++mp) O[mp][dt] = MFMA(vf, __builtin_bit_cast(bf16x8, pk[mp][sub][ks]), O[mp][dt]);
;           }
;         }
;         __builtin_amdgcn_s_setprio(0);
;         __builtin_amdgcn_sched_barrier(0);
;       }
;     ...
;   for (int t = 0; t < nt; t += 2) {
;     if (t + 2 < nt) gload(kt0 + t + 2, rkA, rvA);
;     compute(t, 0);
;     if (t + 1 < nt) lstore(1, rkB, rvB);
;     LDS_BARRIER();
;     if (t + 1 >= nt) break;
;     if (t + 3 < nt) gload(kt0 + t + 3, rkB, rvB);
;     compute(t + 1, 1);
;     if (t + 2 < nt) lstore(0, rkA, rvA);
;     LDS_BARRIER();
.Ldf_s2_1:
	ds_read_b64_tr_b16 v[222:223], v205 offset:32768
	ds_read_b64_tr_b16 v[224:225], v205 offset:34304
	ds_read_b64_tr_b16 v[226:227], v205 offset:32832
	ds_read_b64_tr_b16 v[228:229], v205 offset:34368
	ds_read_b128 v[230:233], v204 offset:45056
	v_exp_f32_e32 v6, v132
	v_exp_f32_e32 v7, v133
	v_exp_f32_e32 v186, v134
	v_exp_f32_e32 v187, v135
	s_waitcnt lgkmcnt(3)
	v_mfma_f32_32x32x16_bf16 v[56:71], v[222:225], v[164:167], v[56:71]
	ds_read_b64_tr_b16 v[234:235], v205 offset:35840
	ds_read_b64_tr_b16 v[236:237], v205 offset:37376
	v_add_f32_e32 v192, v6, v7
	s_waitcnt lgkmcnt(3)
	v_mfma_f32_32x32x16_bf16 v[24:39], v[226:229], v[164:167], v[24:39]
	ds_read_b64_tr_b16 v[222:223], v205 offset:35904
	ds_read_b64_tr_b16 v[224:225], v205 offset:37440
	v_cvt_pk_bf16_f32 v164, v6, v7
	v_add_f32_e32 v192, v192, v186
	v_add_f32_e32 v192, v192, v187
	v_cvt_pk_bf16_f32 v165, v186, v187
	v_exp_f32_e32 v188, v136
	v_exp_f32_e32 v189, v137
	v_exp_f32_e32 v190, v138
	s_waitcnt lgkmcnt(4)
	v_mfma_f32_32x32x16_bf16 v[88:103], v[230:233], v[0:3], v[72:87]
	ds_read_b128 v[226:229], v204 offset:45088
	v_exp_f32_e32 v191, v139
	v_add_f32_e32 v192, v192, v188
	v_add_f32_e32 v192, v192, v189
	v_cvt_pk_bf16_f32 v166, v188, v189
	v_add_f32_e32 v192, v192, v190
	v_add_f32_e32 v192, v192, v191
	v_cvt_pk_bf16_f32 v167, v190, v191
	s_waitcnt lgkmcnt(3)
	v_mfma_f32_32x32x16_bf16 v[56:71], v[234:237], v[172:175], v[56:71]
	ds_read_b64_tr_b16 v[230:231], v205 offset:38912
	ds_read_b64_tr_b16 v[232:233], v205 offset:40448
	v_exp_f32_e32 v6, v140
	v_exp_f32_e32 v7, v141
	v_exp_f32_e32 v186, v142
	v_exp_f32_e32 v187, v143
	v_add_f32_e32 v193, v6, v7
	s_waitcnt lgkmcnt(3)
	v_mfma_f32_32x32x16_bf16 v[24:39], v[222:225], v[172:175], v[24:39]
	ds_read_b64_tr_b16 v[234:235], v205 offset:38976
	ds_read_b64_tr_b16 v[236:237], v205 offset:40512
	v_cvt_pk_bf16_f32 v172, v6, v7
	v_add_f32_e32 v193, v193, v186
	v_add_f32_e32 v193, v193, v187
	v_cvt_pk_bf16_f32 v173, v186, v187
	v_exp_f32_e32 v188, v144
	v_exp_f32_e32 v189, v145
	v_exp_f32_e32 v190, v146
	s_waitcnt lgkmcnt(4)
	v_mfma_f32_32x32x16_bf16 v[88:103], v[226:229], v[120:123], v[88:103]
	ds_read_b128 v[222:225], v204 offset:49664
	v_exp_f32_e32 v191, v147
	v_add_f32_e32 v193, v193, v188
	v_add_f32_e32 v193, v193, v189
	v_cvt_pk_bf16_f32 v174, v188, v189
	v_add_f32_e32 v193, v193, v190
	v_add_f32_e32 v193, v193, v191
	v_cvt_pk_bf16_f32 v175, v190, v191
	s_waitcnt lgkmcnt(3)
	v_mfma_f32_32x32x16_bf16 v[56:71], v[230:233], v[176:179], v[56:71]
	ds_read_b64_tr_b16 v[226:227], v205 offset:41984
	ds_read_b64_tr_b16 v[228:229], v205 offset:43520
	v_exp_f32_e32 v6, v148
	v_exp_f32_e32 v7, v149
	v_exp_f32_e32 v186, v150
	v_exp_f32_e32 v187, v151
	v_add_f32_e32 v194, v6, v7
	s_waitcnt lgkmcnt(3)
	v_mfma_f32_32x32x16_bf16 v[24:39], v[234:237], v[176:179], v[24:39]
	ds_read_b64_tr_b16 v[230:231], v205 offset:42048
	ds_read_b64_tr_b16 v[232:233], v205 offset:43584
	v_cvt_pk_bf16_f32 v176, v6, v7
	v_add_f32_e32 v194, v194, v186
	v_add_f32_e32 v194, v194, v187
	v_cvt_pk_bf16_f32 v177, v186, v187
	v_exp_f32_e32 v188, v152
	v_exp_f32_e32 v189, v153
	v_exp_f32_e32 v190, v154
	s_waitcnt lgkmcnt(4)
	v_mfma_f32_32x32x16_bf16 v[104:119], v[222:225], v[0:3], v[72:87]
	ds_read_b128 v[234:237], v204 offset:49696
	v_exp_f32_e32 v191, v155
	v_add_f32_e32 v194, v194, v188
	v_add_f32_e32 v194, v194, v189
	v_cvt_pk_bf16_f32 v178, v188, v189
	v_add_f32_e32 v194, v194, v190
	v_add_f32_e32 v194, v194, v191
	v_cvt_pk_bf16_f32 v179, v190, v191
	s_waitcnt lgkmcnt(3)
	v_mfma_f32_32x32x16_bf16 v[56:71], v[226:229], v[180:183], v[56:71]
	v_exp_f32_e32 v6, v156
	v_exp_f32_e32 v7, v157
	v_exp_f32_e32 v186, v158
	v_exp_f32_e32 v187, v159
	v_add_f32_e32 v195, v6, v7
	s_waitcnt lgkmcnt(1)
	v_mfma_f32_32x32x16_bf16 v[24:39], v[230:233], v[180:183], v[24:39]
	v_cvt_pk_bf16_f32 v180, v6, v7
	v_add_f32_e32 v195, v195, v186
	v_add_f32_e32 v195, v195, v187
	v_cvt_pk_bf16_f32 v181, v186, v187
	v_exp_f32_e32 v188, v160
	v_exp_f32_e32 v189, v161
	v_exp_f32_e32 v190, v162
	s_waitcnt lgkmcnt(0)
	v_mfma_f32_32x32x16_bf16 v[104:119], v[234:237], v[120:123], v[104:119]
	v_exp_f32_e32 v191, v163
	v_add_f32_e32 v195, v195, v188
	v_add_f32_e32 v195, v195, v189
	v_cvt_pk_bf16_f32 v182, v188, v189
	v_add_f32_e32 v195, v195, v190
	v_add_f32_e32 v195, v195, v191
	v_cvt_pk_bf16_f32 v183, v190, v191
	v_add_f32_e32 v192, v192, v193
	v_add_f32_e32 v194, v194, v195
	v_add_f32_e32 v192, v192, v194
	v_add_f32_e32 v171, v171, v192
	v_max_f32_e32 v201, v201, v192
	s_add_u32 s62, s62, 1
	s_waitcnt lgkmcnt(0)
	s_barrier
	s_cmpk_eq_u32 s62, 0x80
	s_cbranch_scc1 .Ldf_exit
	s_waitcnt vmcnt(0)
	ds_write_b128 v206, v[238:241] offset:23552
	ds_write_b128 v207, v[242:245] offset:11264
	buffer_load_dwordx4 v[246:249], v208, s[8:11], s93 offen
	buffer_load_dwordx4 v[250:253], v208, s[12:15], s28 offen
	s_add_u32 s93, s93, 0x2000
	s_add_u32 s28, s28, 0x2000
	s_cmp_ge_u32 s62, s24
	s_cbranch_scc0 .Ldf_s1_2
	s_cmp_lt_u32 s62, s25
	s_cbranch_scc1 .Ldf_fixa_2
; #define MFMA(a, b, c) __builtin_amdgcn_mfma_f32_32x32x16_bf16((a), (b), (c), 0, 0, 0)
; DI unsigned pk2(float lo, float hi) { f32x2 v = {lo, hi}; b16x2 r = __builtin_convertvector(v, b16x2); return __builtin_bit_cast(unsigned, r); }
; #define LDS_BARRIER() asm volatile("s_waitcnt lgkmcnt(0)\n\ts_barrier" ::: "memory")
; template <int MODE>
; DI void attn_item(const Params& p, int layer, int bh, int qb, char* lds) {
;     ...
;         auto smpass = [&]() {
;           ps = 0.f;
; #pragma unroll
;           for (int sub = 0; sub < 2; ++sub)
; #pragma unroll
;             for (int ks = 0; ks < 2; ++ks)
; #pragma unroll
;               for (int i = 0; i < 4; ++i) {
;                 const float p0 = __builtin_amdgcn_exp2f(s[sub][8 * ks + 2 * i]), p1 = __builtin_amdgcn_exp2f(s[sub][8 * ks + 2 * i + 1]);
;                 ps += p0 + p1; pk[mp][sub][ks][i] = pk2(p0, p1);
;               }
;         };
;         if (first) rebase();
;         smpass();
;         if (!first && __any(!(ps <= PSLIM))) { rebase(); smpass(); }
;         l[mp] += ps;
;         __builtin_amdgcn_sched_barrier(0);
;       }
; #pragma unroll
;       for (int sub = 0; sub < 2; ++sub) {
;         s16x4 vv[8];
;         if (NMAP == 1) {
; #pragma unroll
;           for (int i = 0; i < 8; ++i) vv[i] = vpre[sub * 8 + i];
;         } else {
;           if (sub == 0) trread8<0>(vaddr, vv); else trread8<32 * VSTR>(vaddr, vv);
;         }
;         __builtin_amdgcn_s_setprio(1);
; #pragma unroll
;         for (int ks = 0; ks < 2; ++ks) {
; #pragma unroll
;           for (int dt = 0; dt < 2; ++dt) {
;             s16x4 lo = vv[ks * 4 + dt * 2], hi = vv[ks * 4 + dt * 2 + 1];
;             bf16x8 vf = __builtin_shufflevector(lo, hi, 0, 1, 2, 3, 4, 5, 6, 7);
; #pragma unroll
;             for (int mp = 0; mp < NMAP; ++mp) O[mp][dt] = MFMA(vf, __builtin_bit_cast(bf16x8, pk[mp][sub][ks]), O[mp][dt]);
;           }
;         }
;         __builtin_amdgcn_s_setprio(0);
;         __builtin_amdgcn_sched_barrier(0);
;       }
;     ...
;   for (int t = 0; t < nt; t += 2) {
;     if (t + 2 < nt) gload(kt0 + t + 2, rkA, rvA);
;     compute(t, 0);
;     if (t + 1 < nt) lstore(1, rkB, rvB);
;     LDS_BARRIER();
.Ldf_s1_2:
	ds_read_b64_tr_b16 v[222:223], v205 offset:32768
	ds_read_b64_tr_b16 v[224:225], v205 offset:34304
	ds_read_b64_tr_b16 v[226:227], v205 offset:32832
	ds_read_b64_tr_b16 v[228:229], v205 offset:34368
	ds_read_b128 v[230:233], v204 offset:45120
	v_exp_f32_e32 v6, v88
	v_exp_f32_e32 v7, v89
	v_exp_f32_e32 v186, v90
	v_exp_f32_e32 v187, v91
	s_waitcnt lgkmcnt(3)
	v_mfma_f32_32x32x16_bf16 v[40:55], v[222:225], v[164:167], v[40:55]
	ds_read_b64_tr_b16 v[234:235], v205 offset:35840
	ds_read_b64_tr_b16 v[236:237], v205 offset:37376
	v_add_f32_e32 v192, v6, v7
	s_waitcnt lgkmcnt(3)
	v_mfma_f32_32x32x16_bf16 v[8:23], v[226:229], v[164:167], v[8:23]
	ds_read_b64_tr_b16 v[222:223], v205 offset:35904
	ds_read_b64_tr_b16 v[224:225], v205 offset:37440
	v_cvt_pk_bf16_f32 v164, v6, v7
	v_add_f32_e32 v192, v192, v186
	v_add_f32_e32 v192, v192, v187
	v_cvt_pk_bf16_f32 v165, v186, v187
	v_exp_f32_e32 v188, v92
	v_exp_f32_e32 v189, v93
	v_exp_f32_e32 v190, v94
	s_waitcnt lgkmcnt(4)
	v_mfma_f32_32x32x16_bf16 v[132:147], v[230:233], v[124:127], v[72:87]
	ds_read_b128 v[226:229], v204 offset:45152
	v_exp_f32_e32 v191, v95
	v_add_f32_e32 v192, v192, v188
	v_add_f32_e32 v192, v192, v189
	v_cvt_pk_bf16_f32 v166, v188, v189
	v_add_f32_e32 v192, v192, v190
	v_add_f32_e32 v192, v192, v191
	v_cvt_pk_bf16_f32 v167, v190, v191
	s_waitcnt lgkmcnt(3)
	v_mfma_f32_32x32x16_bf16 v[40:55], v[234:237], v[172:175], v[40:55]
	ds_read_b64_tr_b16 v[230:231], v205 offset:38912
	ds_read_b64_tr_b16 v[232:233], v205 offset:40448
	v_exp_f32_e32 v6, v96
	v_exp_f32_e32 v7, v97
	v_exp_f32_e32 v186, v98
	v_exp_f32_e32 v187, v99
	v_add_f32_e32 v193, v6, v7
	s_waitcnt lgkmcnt(3)
	v_mfma_f32_32x32x16_bf16 v[8:23], v[222:225], v[172:175], v[8:23]
	ds_read_b64_tr_b16 v[234:235], v205 offset:38976
	ds_read_b64_tr_b16 v[236:237], v205 offset:40512
	v_cvt_pk_bf16_f32 v172, v6, v7
	v_add_f32_e32 v193, v193, v186
	v_add_f32_e32 v193, v193, v187
	v_cvt_pk_bf16_f32 v173, v186, v187
	v_exp_f32_e32 v188, v100
	v_exp_f32_e32 v189, v101
	v_exp_f32_e32 v190, v102
	s_waitcnt lgkmcnt(4)
	v_mfma_f32_32x32x16_bf16 v[132:147], v[226:229], v[128:131], v[132:147]
	ds_read_b128 v[222:225], v204 offset:49728
	v_exp_f32_e32 v191, v103
	v_add_f32_e32 v193, v193, v188
	v_add_f32_e32 v193, v193, v189
	v_cvt_pk_bf16_f32 v174, v188, v189
	v_add_f32_e32 v193, v193, v190
	v_add_f32_e32 v193, v193, v191
	v_cvt_pk_bf16_f32 v175, v190, v191
	s_waitcnt lgkmcnt(3)
	v_mfma_f32_32x32x16_bf16 v[40:55], v[230:233], v[176:179], v[40:55]
	ds_read_b64_tr_b16 v[226:227], v205 offset:41984
	ds_read_b64_tr_b16 v[228:229], v205 offset:43520
	v_exp_f32_e32 v6, v104
	v_exp_f32_e32 v7, v105
	v_exp_f32_e32 v186, v106
	v_exp_f32_e32 v187, v107
	v_add_f32_e32 v194, v6, v7
	s_waitcnt lgkmcnt(3)
	v_mfma_f32_32x32x16_bf16 v[8:23], v[234:237], v[176:179], v[8:23]
	ds_read_b64_tr_b16 v[230:231], v205 offset:42048
	ds_read_b64_tr_b16 v[232:233], v205 offset:43584
	v_cvt_pk_bf16_f32 v176, v6, v7
	v_add_f32_e32 v194, v194, v186
	v_add_f32_e32 v194, v194, v187
	v_cvt_pk_bf16_f32 v177, v186, v187
	v_exp_f32_e32 v188, v108
	v_exp_f32_e32 v189, v109
	v_exp_f32_e32 v190, v110
	s_waitcnt lgkmcnt(4)
	v_mfma_f32_32x32x16_bf16 v[148:163], v[222:225], v[124:127], v[72:87]
	ds_read_b128 v[234:237], v204 offset:49760
	v_exp_f32_e32 v191, v111
	v_add_f32_e32 v194, v194, v188
	v_add_f32_e32 v194, v194, v189
	v_cvt_pk_bf16_f32 v178, v188, v189
	v_add_f32_e32 v194, v194, v190
	v_add_f32_e32 v194, v194, v191
	v_cvt_pk_bf16_f32 v179, v190, v191
	s_waitcnt lgkmcnt(3)
	v_mfma_f32_32x32x16_bf16 v[40:55], v[226:229], v[180:183], v[40:55]
	v_exp_f32_e32 v6, v112
	v_exp_f32_e32 v7, v113
	v_exp_f32_e32 v186, v114
	v_exp_f32_e32 v187, v115
	v_add_f32_e32 v195, v6, v7
	s_waitcnt lgkmcnt(1)
	v_mfma_f32_32x32x16_bf16 v[8:23], v[230:233], v[180:183], v[8:23]
	v_cvt_pk_bf16_f32 v180, v6, v7
	v_add_f32_e32 v195, v195, v186
	v_add_f32_e32 v195, v195, v187
	v_cvt_pk_bf16_f32 v181, v186, v187
	v_exp_f32_e32 v188, v116
	v_exp_f32_e32 v189, v117
	v_exp_f32_e32 v190, v118
	s_waitcnt lgkmcnt(0)
	v_mfma_f32_32x32x16_bf16 v[148:163], v[234:237], v[128:131], v[148:163]
	v_exp_f32_e32 v191, v119
	v_add_f32_e32 v195, v195, v188
	v_add_f32_e32 v195, v195, v189
	v_cvt_pk_bf16_f32 v182, v188, v189
	v_add_f32_e32 v195, v195, v190
	v_add_f32_e32 v195, v195, v191
	v_cvt_pk_bf16_f32 v183, v190, v191
	v_add_f32_e32 v192, v192, v193
	v_add_f32_e32 v194, v194, v195
	v_add_f32_e32 v192, v192, v194
	v_add_f32_e32 v170, v170, v192
	v_max_f32_e32 v201, v201, v192
	s_add_u32 s4, s62, 1
	s_cmp_eq_u32 s4, s24
	s_cbranch_scc1 .Ldf_c0n_2
	s_cmp_eq_u32 s4, s25
	s_cbranch_scc1 .Ldf_c0r_2

; #define MFMA(a, b, c) __builtin_amdgcn_mfma_f32_32x32x16_bf16((a), (b), (c), 0, 0, 0)
; DI unsigned pk2(float lo, float hi) { f32x2 v = {lo, hi}; b16x2 r = __builtin_convertvector(v, b16x2); return __builtin_bit_cast(unsigned, r); }
; #define LDS_BARRIER() asm volatile("s_waitcnt lgkmcnt(0)\n\ts_barrier" ::: "memory")
; template <int MODE>
; DI void attn_item(const Params& p, int layer, int bh, int qb, char* lds) {
;     ...
;         auto smpass = [&]() {
;           ps = 0.f;
; #pragma unroll
;           for (int sub = 0; sub < 2; ++sub)
; #pragma unroll
;             for (int ks = 0; ks < 2; ++ks)
; #pragma unroll
;               for (int i = 0; i < 4; ++i) {
;                 const float p0 = __builtin_amdgcn_exp2f(s[sub][8 * ks + 2 * i]), p1 = __builtin_amdgcn_exp2f(s[sub][8 * ks + 2 * i + 1]);
;                 ps += p0 + p1; pk[mp][sub][ks][i] = pk2(p0, p1);
;               }
;         };
;         if (first) rebase();
;         smpass();
;         if (!first && __any(!(ps <= PSLIM))) { rebase(); smpass(); }
;         l[mp] += ps;
;         __builtin_amdgcn_sched_barrier(0);
;       }
; #pragma unroll
;       for (int sub = 0; sub < 2; ++sub) {
;         s16x4 vv[8];
;         if (NMAP == 1) {
; #pragma unroll
;           for (int i = 0; i < 8; ++i) vv[i] = vpre[sub * 8 + i];
;         } else {
;           if (sub == 0) trread8<0>(vaddr, vv); else trread8<32 * VSTR>(vaddr, vv);
;         }
;         __builtin_amdgcn_s_setprio(1);
; #pragma unroll
;         for (int ks = 0; ks < 2; ++ks) {
; #pragma unroll
;           for (int dt = 0; dt < 2; ++dt) {
;             s16x4 lo = vv[ks * 4 + dt * 2], hi = vv[ks * 4 + dt * 2 + 1];
;             bf16x8 vf = __builtin_shufflevector(lo, hi, 0, 1, 2, 3, 4, 5, 6, 7);
; #pragma unroll
;             for (int mp = 0; mp < NMAP; ++mp) O[mp][dt] = MFMA(vf, __builtin_bit_cast(bf16x8, pk[mp][sub][ks]), O[mp][dt]);
;           }
;         }
;         __builtin_amdgcn_s_setprio(0);
;         __builtin_amdgcn_sched_barrier(0);
;       }
;     ...
;   for (int t = 0; t < nt; t += 2) {
;     if (t + 2 < nt) gload(kt0 + t + 2, rkA, rvA);
;     compute(t, 0);
;     if (t + 1 < nt) lstore(1, rkB, rvB);
;     LDS_BARRIER();
;     if (t + 1 >= nt) break;
;     if (t + 3 < nt) gload(kt0 + t + 3, rkB, rvB);
;     compute(t + 1, 1);
;     if (t + 2 < nt) lstore(0, rkA, rvA);
;     LDS_BARRIER();
.Ldf_s2_2:
	ds_read_b64_tr_b16 v[222:223], v205 offset:54272
	ds_read_b64_tr_b16 v[224:225], v205 offset:55808
	ds_read_b64_tr_b16 v[226:227], v205 offset:54336
	ds_read_b64_tr_b16 v[228:229], v205 offset:55872
	ds_read_b128 v[230:233], v204 offset:2048
	v_exp_f32_e32 v6, v132
	v_exp_f32_e32 v7, v133
	v_exp_f32_e32 v186, v134
	v_exp_f32_e32 v187, v135
	s_waitcnt lgkmcnt(3)
	v_mfma_f32_32x32x16_bf16 v[56:71], v[222:225], v[164:167], v[56:71]
	ds_read_b64_tr_b16 v[234:235], v205 offset:57344
	ds_read_b64_tr_b16 v[236:237], v205 offset:58880
	v_add_f32_e32 v192, v6, v7
	s_waitcnt lgkmcnt(3)
	v_mfma_f32_32x32x16_bf16 v[24:39], v[226:229], v[164:167], v[24:39]
	ds_read_b64_tr_b16 v[222:223], v205 offset:57408
	ds_read_b64_tr_b16 v[224:225], v205 offset:58944
	v_cvt_pk_bf16_f32 v164, v6, v7
	v_add_f32_e32 v192, v192, v186
	v_add_f32_e32 v192, v192, v187
	v_cvt_pk_bf16_f32 v165, v186, v187
	v_exp_f32_e32 v188, v136
	v_exp_f32_e32 v189, v137
	v_exp_f32_e32 v190, v138
	s_waitcnt lgkmcnt(4)
	v_mfma_f32_32x32x16_bf16 v[88:103], v[230:233], v[0:3], v[72:87]
	ds_read_b128 v[226:229], v204 offset:2080
	v_exp_f32_e32 v191, v139
	v_add_f32_e32 v192, v192, v188
	v_add_f32_e32 v192, v192, v189
	v_cvt_pk_bf16_f32 v166, v188, v189
	v_add_f32_e32 v192, v192, v190
	v_add_f32_e32 v192, v192, v191
	v_cvt_pk_bf16_f32 v167, v190, v191
	s_waitcnt lgkmcnt(3)
	v_mfma_f32_32x32x16_bf16 v[56:71], v[234:237], v[172:175], v[56:71]
	ds_read_b64_tr_b16 v[230:231], v205 offset:60416
	ds_read_b64_tr_b16 v[232:233], v205 offset:61952
	v_exp_f32_e32 v6, v140
	v_exp_f32_e32 v7, v141
	v_exp_f32_e32 v186, v142
	v_exp_f32_e32 v187, v143
	v_add_f32_e32 v193, v6, v7
	s_waitcnt lgkmcnt(3)
	v_mfma_f32_32x32x16_bf16 v[24:39], v[222:225], v[172:175], v[24:39]
	ds_read_b64_tr_b16 v[234:235], v205 offset:60480
	ds_read_b64_tr_b16 v[236:237], v205 offset:62016
	v_cvt_pk_bf16_f32 v172, v6, v7
	v_add_f32_e32 v193, v193, v186
	v_add_f32_e32 v193, v193, v187
	v_cvt_pk_bf16_f32 v173, v186, v187
	v_exp_f32_e32 v188, v144
	v_exp_f32_e32 v189, v145
	v_exp_f32_e32 v190, v146
	s_waitcnt lgkmcnt(4)
	v_mfma_f32_32x32x16_bf16 v[88:103], v[226:229], v[120:123], v[88:103]
	ds_read_b128 v[222:225], v204 offset:6656
	v_exp_f32_e32 v191, v147
	v_add_f32_e32 v193, v193, v188
	v_add_f32_e32 v193, v193, v189
	v_cvt_pk_bf16_f32 v174, v188, v189
	v_add_f32_e32 v193, v193, v190
	v_add_f32_e32 v193, v193, v191
	v_cvt_pk_bf16_f32 v175, v190, v191
	s_waitcnt lgkmcnt(3)
	v_mfma_f32_32x32x16_bf16 v[56:71], v[230:233], v[176:179], v[56:71]
	ds_read_b64_tr_b16 v[226:227], v205 offset:63488
	ds_read_b64_tr_b16 v[228:229], v205 offset:65024
	v_exp_f32_e32 v6, v148
	v_exp_f32_e32 v7, v149
	v_exp_f32_e32 v186, v150
	v_exp_f32_e32 v187, v151
	v_add_f32_e32 v194, v6, v7
	s_waitcnt lgkmcnt(3)
	v_mfma_f32_32x32x16_bf16 v[24:39], v[234:237], v[176:179], v[24:39]
	ds_read_b64_tr_b16 v[230:231], v205 offset:63552
	ds_read_b64_tr_b16 v[232:233], v205 offset:65088
	v_cvt_pk_bf16_f32 v176, v6, v7
	v_add_f32_e32 v194, v194, v186
	v_add_f32_e32 v194, v194, v187
	v_cvt_pk_bf16_f32 v177, v186, v187
	v_exp_f32_e32 v188, v152
	v_exp_f32_e32 v189, v153
	v_exp_f32_e32 v190, v154
	s_waitcnt lgkmcnt(4)
	v_mfma_f32_32x32x16_bf16 v[104:119], v[222:225], v[0:3], v[72:87]
	ds_read_b128 v[234:237], v204 offset:6688
	v_exp_f32_e32 v191, v155
	v_add_f32_e32 v194, v194, v188
	v_add_f32_e32 v194, v194, v189
	v_cvt_pk_bf16_f32 v178, v188, v189
	v_add_f32_e32 v194, v194, v190
	v_add_f32_e32 v194, v194, v191
	v_cvt_pk_bf16_f32 v179, v190, v191
	s_waitcnt lgkmcnt(3)
	v_mfma_f32_32x32x16_bf16 v[56:71], v[226:229], v[180:183], v[56:71]
	v_exp_f32_e32 v6, v156
	v_exp_f32_e32 v7, v157
	v_exp_f32_e32 v186, v158
	v_exp_f32_e32 v187, v159
	v_add_f32_e32 v195, v6, v7
	s_waitcnt lgkmcnt(1)
	v_mfma_f32_32x32x16_bf16 v[24:39], v[230:233], v[180:183], v[24:39]
	v_cvt_pk_bf16_f32 v180, v6, v7
	v_add_f32_e32 v195, v195, v186
	v_add_f32_e32 v195, v195, v187
	v_cvt_pk_bf16_f32 v181, v186, v187
	v_exp_f32_e32 v188, v160
	v_exp_f32_e32 v189, v161
	v_exp_f32_e32 v190, v162
	s_waitcnt lgkmcnt(0)
	v_mfma_f32_32x32x16_bf16 v[104:119], v[234:237], v[120:123], v[104:119]
	v_exp_f32_e32 v191, v163
	v_add_f32_e32 v195, v195, v188
	v_add_f32_e32 v195, v195, v189
	v_cvt_pk_bf16_f32 v182, v188, v189
	v_add_f32_e32 v195, v195, v190
	v_add_f32_e32 v195, v195, v191
	v_cvt_pk_bf16_f32 v183, v190, v191
	v_add_f32_e32 v192, v192, v193
	v_add_f32_e32 v194, v194, v195
	v_add_f32_e32 v192, v192, v194
	v_add_f32_e32 v171, v171, v192
	v_max_f32_e32 v201, v201, v192
	s_add_u32 s62, s62, 1
	s_waitcnt lgkmcnt(0)
	s_barrier
	s_waitcnt vmcnt(0)
	ds_write_b128 v206, v[246:249] offset:45056
	ds_write_b128 v207, v[250:253] offset:32768
	buffer_load_dwordx4 v[238:241], v208, s[8:11], s93 offen
	buffer_load_dwordx4 v[242:245], v208, s[12:15], s28 offen
	s_add_u32 s93, s93, 0x2000
	s_add_u32 s28, s28, 0x2000
	s_cmp_ge_u32 s62, s24
	s_cbranch_scc0 .Ldf_s1_3
	s_cmp_lt_u32 s62, s25
	s_cbranch_scc1 .Ldf_fixa_3

; #define MFMA(a, b, c) __builtin_amdgcn_mfma_f32_32x32x16_bf16((a), (b), (c), 0, 0, 0)
; DI unsigned pk2(float lo, float hi) { f32x2 v = {lo, hi}; b16x2 r = __builtin_convertvector(v, b16x2); return __builtin_bit_cast(unsigned, r); }
; #define LDS_BARRIER() asm volatile("s_waitcnt lgkmcnt(0)\n\ts_barrier" ::: "memory")
; template <int MODE>
; DI void attn_item(const Params& p, int layer, int bh, int qb, char* lds) {
;     ...
;         auto smpass = [&]() {
;           ps = 0.f;
; #pragma unroll
;           for (int sub = 0; sub < 2; ++sub)
; #pragma unroll
;             for (int ks = 0; ks < 2; ++ks)
; #pragma unroll
;               for (int i = 0; i < 4; ++i) {
;                 const float p0 = __builtin_amdgcn_exp2f(s[sub][8 * ks + 2 * i]), p1 = __builtin_amdgcn_exp2f(s[sub][8 * ks + 2 * i + 1]);
;                 ps += p0 + p1; pk[mp][sub][ks][i] = pk2(p0, p1);
;               }
;         };
;         if (first) rebase();
;         smpass();
;         if (!first && __any(!(ps <= PSLIM))) { rebase(); smpass(); }
;         l[mp] += ps;
;         __builtin_amdgcn_sched_barrier(0);
;       }
; #pragma unroll
;       for (int sub = 0; sub < 2; ++sub) {
;         s16x4 vv[8];
;         if (NMAP == 1) {
; #pragma unroll
;           for (int i = 0; i < 8; ++i) vv[i] = vpre[sub * 8 + i];
;         } else {
;           if (sub == 0) trread8<0>(vaddr, vv); else trread8<32 * VSTR>(vaddr, vv);
;         }
;         __builtin_amdgcn_s_setprio(1);
; #pragma unroll
;         for (int ks = 0; ks < 2; ++ks) {
; #pragma unroll
;           for (int dt = 0; dt < 2; ++dt) {
;             s16x4 lo = vv[ks * 4 + dt * 2], hi = vv[ks * 4 + dt * 2 + 1];
;             bf16x8 vf = __builtin_shufflevector(lo, hi, 0, 1, 2, 3, 4, 5, 6, 7);
; #pragma unroll
;             for (int mp = 0; mp < NMAP; ++mp) O[mp][dt] = MFMA(vf, __builtin_bit_cast(bf16x8, pk[mp][sub][ks]), O[mp][dt]);
;           }
;         }
;         __builtin_amdgcn_s_setprio(0);
;         __builtin_amdgcn_sched_barrier(0);
;       }
;     ...
;   for (int t = 0; t < nt; t += 2) {
;     if (t + 2 < nt) gload(kt0 + t + 2, rkA, rvA);
;     compute(t, 0);
;     if (t + 1 < nt) lstore(1, rkB, rvB);
;     LDS_BARRIER();
;     if (t + 1 >= nt) break;
;     if (t + 3 < nt) gload(kt0 + t + 3, rkB, rvB);
;     compute(t + 1, 1);
;     if (t + 2 < nt) lstore(0, rkA, rvA);
;     LDS_BARRIER();
.Ldf_s2_3:
	ds_read_b64_tr_b16 v[222:223], v205 offset:11264
	ds_read_b64_tr_b16 v[224:225], v205 offset:12800
	ds_read_b64_tr_b16 v[226:227], v205 offset:11328
	ds_read_b64_tr_b16 v[228:229], v205 offset:12864
	ds_read_b128 v[230:233], v204 offset:23552
	v_exp_f32_e32 v6, v132
	v_exp_f32_e32 v7, v133
	v_exp_f32_e32 v186, v134
	v_exp_f32_e32 v187, v135
	s_waitcnt lgkmcnt(3)
	v_mfma_f32_32x32x16_bf16 v[56:71], v[222:225], v[164:167], v[56:71]
	ds_read_b64_tr_b16 v[234:235], v205 offset:14336
	ds_read_b64_tr_b16 v[236:237], v205 offset:15872
	v_add_f32_e32 v192, v6, v7
	s_waitcnt lgkmcnt(3)
	v_mfma_f32_32x32x16_bf16 v[24:39], v[226:229], v[164:167], v[24:39]
	ds_read_b64_tr_b16 v[222:223], v205 offset:14400
	ds_read_b64_tr_b16 v[224:225], v205 offset:15936
	v_cvt_pk_bf16_f32 v164, v6, v7
	v_add_f32_e32 v192, v192, v186
	v_add_f32_e32 v192, v192, v187
	v_cvt_pk_bf16_f32 v165, v186, v187
	v_exp_f32_e32 v188, v136
	v_exp_f32_e32 v189, v137
	v_exp_f32_e32 v190, v138
	s_waitcnt lgkmcnt(4)
	v_mfma_f32_32x32x16_bf16 v[88:103], v[230:233], v[0:3], v[72:87]
	ds_read_b128 v[226:229], v204 offset:23584
	v_exp_f32_e32 v191, v139
	v_add_f32_e32 v192, v192, v188
	v_add_f32_e32 v192, v192, v189
	v_cvt_pk_bf16_f32 v166, v188, v189
	v_add_f32_e32 v192, v192, v190
	v_add_f32_e32 v192, v192, v191
	v_cvt_pk_bf16_f32 v167, v190, v191
	s_waitcnt lgkmcnt(3)
	v_mfma_f32_32x32x16_bf16 v[56:71], v[234:237], v[172:175], v[56:71]
	ds_read_b64_tr_b16 v[230:231], v205 offset:17408
	ds_read_b64_tr_b16 v[232:233], v205 offset:18944
	v_exp_f32_e32 v6, v140
	v_exp_f32_e32 v7, v141
	v_exp_f32_e32 v186, v142
	v_exp_f32_e32 v187, v143
	v_add_f32_e32 v193, v6, v7
	s_waitcnt lgkmcnt(3)
	v_mfma_f32_32x32x16_bf16 v[24:39], v[222:225], v[172:175], v[24:39]
	ds_read_b64_tr_b16 v[234:235], v205 offset:17472
	ds_read_b64_tr_b16 v[236:237], v205 offset:19008
	v_cvt_pk_bf16_f32 v172, v6, v7
	v_add_f32_e32 v193, v193, v186
	v_add_f32_e32 v193, v193, v187
	v_cvt_pk_bf16_f32 v173, v186, v187
	v_exp_f32_e32 v188, v144
	v_exp_f32_e32 v189, v145
	v_exp_f32_e32 v190, v146
	s_waitcnt lgkmcnt(4)
	v_mfma_f32_32x32x16_bf16 v[88:103], v[226:229], v[120:123], v[88:103]
	ds_read_b128 v[222:225], v204 offset:28160
	v_exp_f32_e32 v191, v147
	v_add_f32_e32 v193, v193, v188
	v_add_f32_e32 v193, v193, v189
	v_cvt_pk_bf16_f32 v174, v188, v189
	v_add_f32_e32 v193, v193, v190
	v_add_f32_e32 v193, v193, v191
	v_cvt_pk_bf16_f32 v175, v190, v191
	s_waitcnt lgkmcnt(3)
	v_mfma_f32_32x32x16_bf16 v[56:71], v[230:233], v[176:179], v[56:71]
	ds_read_b64_tr_b16 v[226:227], v205 offset:20480
	ds_read_b64_tr_b16 v[228:229], v205 offset:22016
	v_exp_f32_e32 v6, v148
	v_exp_f32_e32 v7, v149
	v_exp_f32_e32 v186, v150
	v_exp_f32_e32 v187, v151
	v_add_f32_e32 v194, v6, v7
	s_waitcnt lgkmcnt(3)
	v_mfma_f32_32x32x16_bf16 v[24:39], v[234:237], v[176:179], v[24:39]
	ds_read_b64_tr_b16 v[230:231], v205 offset:20544
	ds_read_b64_tr_b16 v[232:233], v205 offset:22080
	v_cvt_pk_bf16_f32 v176, v6, v7
	v_add_f32_e32 v194, v194, v186
	v_add_f32_e32 v194, v194, v187
	v_cvt_pk_bf16_f32 v177, v186, v187
	v_exp_f32_e32 v188, v152
	v_exp_f32_e32 v189, v153
	v_exp_f32_e32 v190, v154
	s_waitcnt lgkmcnt(4)
	v_mfma_f32_32x32x16_bf16 v[104:119], v[222:225], v[0:3], v[72:87]
	ds_read_b128 v[234:237], v204 offset:28192
	v_exp_f32_e32 v191, v155
	v_add_f32_e32 v194, v194, v188
	v_add_f32_e32 v194, v194, v189
	v_cvt_pk_bf16_f32 v178, v188, v189
	v_add_f32_e32 v194, v194, v190
	v_add_f32_e32 v194, v194, v191
	v_cvt_pk_bf16_f32 v179, v190, v191
	s_waitcnt lgkmcnt(3)
	v_mfma_f32_32x32x16_bf16 v[56:71], v[226:229], v[180:183], v[56:71]
	v_exp_f32_e32 v6, v156
	v_exp_f32_e32 v7, v157
	v_exp_f32_e32 v186, v158
	v_exp_f32_e32 v187, v159
	v_add_f32_e32 v195, v6, v7
	s_waitcnt lgkmcnt(1)
	v_mfma_f32_32x32x16_bf16 v[24:39], v[230:233], v[180:183], v[24:39]
	v_cvt_pk_bf16_f32 v180, v6, v7
	v_add_f32_e32 v195, v195, v186
	v_add_f32_e32 v195, v195, v187
	v_cvt_pk_bf16_f32 v181, v186, v187
	v_exp_f32_e32 v188, v160
	v_exp_f32_e32 v189, v161
	v_exp_f32_e32 v190, v162
	s_waitcnt lgkmcnt(0)
	v_mfma_f32_32x32x16_bf16 v[104:119], v[234:237], v[120:123], v[104:119]
	v_exp_f32_e32 v191, v163
	v_add_f32_e32 v195, v195, v188
	v_add_f32_e32 v195, v195, v189
	v_cvt_pk_bf16_f32 v182, v188, v189
	v_add_f32_e32 v195, v195, v190
	v_add_f32_e32 v195, v195, v191
	v_cvt_pk_bf16_f32 v183, v190, v191
	v_add_f32_e32 v192, v192, v193
	v_add_f32_e32 v194, v194, v195
	v_add_f32_e32 v192, v192, v194
	v_add_f32_e32 v171, v171, v192
	v_max_f32_e32 v201, v201, v192
	s_add_u32 s62, s62, 1
	s_waitcnt lgkmcnt(0)
	s_barrier
	s_waitcnt vmcnt(0)
	ds_write_b128 v206, v[238:241] offset:2048
	ds_write_b128 v207, v[242:245] offset:54272
	buffer_load_dwordx4 v[246:249], v208, s[8:11], s93 offen
	buffer_load_dwordx4 v[250:253], v208, s[12:15], s28 offen
	s_add_u32 s93, s93, 0x2000
	s_add_u32 s28, s28, 0x2000
	s_cmp_ge_u32 s62, s24
	s_cbranch_scc0 .Ldf_s1_4
	s_cmp_lt_u32 s62, s25
	s_cbranch_scc1 .Ldf_fixa_4

; #define MFMA(a, b, c) __builtin_amdgcn_mfma_f32_32x32x16_bf16((a), (b), (c), 0, 0, 0)
; DI unsigned pk2(float lo, float hi) { f32x2 v = {lo, hi}; b16x2 r = __builtin_convertvector(v, b16x2); return __builtin_bit_cast(unsigned, r); }
; #define LDS_BARRIER() asm volatile("s_waitcnt lgkmcnt(0)\n\ts_barrier" ::: "memory")
; template <int MODE>
; DI void attn_item(const Params& p, int layer, int bh, int qb, char* lds) {
;     ...
;         auto smpass = [&]() {
;           ps = 0.f;
; #pragma unroll
;           for (int sub = 0; sub < 2; ++sub)
; #pragma unroll
;             for (int ks = 0; ks < 2; ++ks)
; #pragma unroll
;               for (int i = 0; i < 4; ++i) {
;                 const float p0 = __builtin_amdgcn_exp2f(s[sub][8 * ks + 2 * i]), p1 = __builtin_amdgcn_exp2f(s[sub][8 * ks + 2 * i + 1]);
;                 ps += p0 + p1; pk[mp][sub][ks][i] = pk2(p0, p1);
;               }
;         };
;         if (first) rebase();
;         smpass();
;         if (!first && __any(!(ps <= PSLIM))) { rebase(); smpass(); }
;         l[mp] += ps;
;         __builtin_amdgcn_sched_barrier(0);
;       }
; #pragma unroll
;       for (int sub = 0; sub < 2; ++sub) {
;         s16x4 vv[8];
;         if (NMAP == 1) {
; #pragma unroll
;           for (int i = 0; i < 8; ++i) vv[i] = vpre[sub * 8 + i];
;         } else {
;           if (sub == 0) trread8<0>(vaddr, vv); else trread8<32 * VSTR>(vaddr, vv);
;         }
;         __builtin_amdgcn_s_setprio(1);
; #pragma unroll
;         for (int ks = 0; ks < 2; ++ks) {
; #pragma unroll
;           for (int dt = 0; dt < 2; ++dt) {
;             s16x4 lo = vv[ks * 4 + dt * 2], hi = vv[ks * 4 + dt * 2 + 1];
;             bf16x8 vf = __builtin_shufflevector(lo, hi, 0, 1, 2, 3, 4, 5, 6, 7);
; #pragma unroll
;             for (int mp = 0; mp < NMAP; ++mp) O[mp][dt] = MFMA(vf, __builtin_bit_cast(bf16x8, pk[mp][sub][ks]), O[mp][dt]);
;           }
;         }
;         __builtin_amdgcn_s_setprio(0);
;         __builtin_amdgcn_sched_barrier(0);
;       }
;     ...
;   for (int t = 0; t < nt; t += 2) {
;     if (t + 2 < nt) gload(kt0 + t + 2, rkA, rvA);
;     compute(t, 0);
;     if (t + 1 < nt) lstore(1, rkB, rvB);
;     LDS_BARRIER();
;     if (t + 1 >= nt) break;
;     if (t + 3 < nt) gload(kt0 + t + 3, rkB, rvB);
;     compute(t + 1, 1);
;     if (t + 2 < nt) lstore(0, rkA, rvA);
;     LDS_BARRIER();
.Ldf_s2_4:
	ds_read_b64_tr_b16 v[222:223], v205 offset:32768
	ds_read_b64_tr_b16 v[224:225], v205 offset:34304
	ds_read_b64_tr_b16 v[226:227], v205 offset:32832
	ds_read_b64_tr_b16 v[228:229], v205 offset:34368
	ds_read_b128 v[230:233], v204 offset:45056
	v_exp_f32_e32 v6, v132
	v_exp_f32_e32 v7, v133
	v_exp_f32_e32 v186, v134
	v_exp_f32_e32 v187, v135
	s_waitcnt lgkmcnt(3)
	v_mfma_f32_32x32x16_bf16 v[56:71], v[222:225], v[164:167], v[56:71]
	ds_read_b64_tr_b16 v[234:235], v205 offset:35840
	ds_read_b64_tr_b16 v[236:237], v205 offset:37376
	v_add_f32_e32 v192, v6, v7
	s_waitcnt lgkmcnt(3)
	v_mfma_f32_32x32x16_bf16 v[24:39], v[226:229], v[164:167], v[24:39]
	ds_read_b64_tr_b16 v[222:223], v205 offset:35904
	ds_read_b64_tr_b16 v[224:225], v205 offset:37440
	v_cvt_pk_bf16_f32 v164, v6, v7
	v_add_f32_e32 v192, v192, v186
	v_add_f32_e32 v192, v192, v187
	v_cvt_pk_bf16_f32 v165, v186, v187
	v_exp_f32_e32 v188, v136
	v_exp_f32_e32 v189, v137
	v_exp_f32_e32 v190, v138
	s_waitcnt lgkmcnt(4)
	v_mfma_f32_32x32x16_bf16 v[88:103], v[230:233], v[0:3], v[72:87]
	ds_read_b128 v[226:229], v204 offset:45088
	v_exp_f32_e32 v191, v139
	v_add_f32_e32 v192, v192, v188
	v_add_f32_e32 v192, v192, v189
	v_cvt_pk_bf16_f32 v166, v188, v189
	v_add_f32_e32 v192, v192, v190
	v_add_f32_e32 v192, v192, v191
	v_cvt_pk_bf16_f32 v167, v190, v191
	s_waitcnt lgkmcnt(3)
	v_mfma_f32_32x32x16_bf16 v[56:71], v[234:237], v[172:175], v[56:71]
	ds_read_b64_tr_b16 v[230:231], v205 offset:38912
	ds_read_b64_tr_b16 v[232:233], v205 offset:40448
	v_exp_f32_e32 v6, v140
	v_exp_f32_e32 v7, v141
	v_exp_f32_e32 v186, v142
	v_exp_f32_e32 v187, v143
	v_add_f32_e32 v193, v6, v7
	s_waitcnt lgkmcnt(3)
	v_mfma_f32_32x32x16_bf16 v[24:39], v[222:225], v[172:175], v[24:39]
	ds_read_b64_tr_b16 v[234:235], v205 offset:38976
	ds_read_b64_tr_b16 v[236:237], v205 offset:40512
	v_cvt_pk_bf16_f32 v172, v6, v7
	v_add_f32_e32 v193, v193, v186
	v_add_f32_e32 v193, v193, v187
	v_cvt_pk_bf16_f32 v173, v186, v187
	v_exp_f32_e32 v188, v144
	v_exp_f32_e32 v189, v145
	v_exp_f32_e32 v190, v146
	s_waitcnt lgkmcnt(4)
	v_mfma_f32_32x32x16_bf16 v[88:103], v[226:229], v[120:123], v[88:103]
	ds_read_b128 v[222:225], v204 offset:49664
	v_exp_f32_e32 v191, v147
	v_add_f32_e32 v193, v193, v188
	v_add_f32_e32 v193, v193, v189
	v_cvt_pk_bf16_f32 v174, v188, v189
	v_add_f32_e32 v193, v193, v190
	v_add_f32_e32 v193, v193, v191
	v_cvt_pk_bf16_f32 v175, v190, v191
	s_waitcnt lgkmcnt(3)
	v_mfma_f32_32x32x16_bf16 v[56:71], v[230:233], v[176:179], v[56:71]
	ds_read_b64_tr_b16 v[226:227], v205 offset:41984
	ds_read_b64_tr_b16 v[228:229], v205 offset:43520
	v_exp_f32_e32 v6, v148
	v_exp_f32_e32 v7, v149
	v_exp_f32_e32 v186, v150
	v_exp_f32_e32 v187, v151
	v_add_f32_e32 v194, v6, v7
	s_waitcnt lgkmcnt(3)
	v_mfma_f32_32x32x16_bf16 v[24:39], v[234:237], v[176:179], v[24:39]
	ds_read_b64_tr_b16 v[230:231], v205 offset:42048
	ds_read_b64_tr_b16 v[232:233], v205 offset:43584
	v_cvt_pk_bf16_f32 v176, v6, v7
	v_add_f32_e32 v194, v194, v186
	v_add_f32_e32 v194, v194, v187
	v_cvt_pk_bf16_f32 v177, v186, v187
	v_exp_f32_e32 v188, v152
	v_exp_f32_e32 v189, v153
	v_exp_f32_e32 v190, v154
	s_waitcnt lgkmcnt(4)
	v_mfma_f32_32x32x16_bf16 v[104:119], v[222:225], v[0:3], v[72:87]
	ds_read_b128 v[234:237], v204 offset:49696
	v_exp_f32_e32 v191, v155
	v_add_f32_e32 v194, v194, v188
	v_add_f32_e32 v194, v194, v189
	v_cvt_pk_bf16_f32 v178, v188, v189
	v_add_f32_e32 v194, v194, v190
	v_add_f32_e32 v194, v194, v191
	v_cvt_pk_bf16_f32 v179, v190, v191
	s_waitcnt lgkmcnt(3)
	v_mfma_f32_32x32x16_bf16 v[56:71], v[226:229], v[180:183], v[56:71]
	v_exp_f32_e32 v6, v156
	v_exp_f32_e32 v7, v157
	v_exp_f32_e32 v186, v158
	v_exp_f32_e32 v187, v159
	v_add_f32_e32 v195, v6, v7
	s_waitcnt lgkmcnt(1)
	v_mfma_f32_32x32x16_bf16 v[24:39], v[230:233], v[180:183], v[24:39]
	v_cvt_pk_bf16_f32 v180, v6, v7
	v_add_f32_e32 v195, v195, v186
	v_add_f32_e32 v195, v195, v187
	v_cvt_pk_bf16_f32 v181, v186, v187
	v_exp_f32_e32 v188, v160
	v_exp_f32_e32 v189, v161
	v_exp_f32_e32 v190, v162
	s_waitcnt lgkmcnt(0)
	v_mfma_f32_32x32x16_bf16 v[104:119], v[234:237], v[120:123], v[104:119]
	v_exp_f32_e32 v191, v163
	v_add_f32_e32 v195, v195, v188
	v_add_f32_e32 v195, v195, v189
	v_cvt_pk_bf16_f32 v182, v188, v189
	v_add_f32_e32 v195, v195, v190
	v_add_f32_e32 v195, v195, v191
	v_cvt_pk_bf16_f32 v183, v190, v191
	v_add_f32_e32 v192, v192, v193
	v_add_f32_e32 v194, v194, v195
	v_add_f32_e32 v192, v192, v194
	v_add_f32_e32 v171, v171, v192
	v_max_f32_e32 v201, v201, v192
	s_add_u32 s62, s62, 1
	s_waitcnt lgkmcnt(0)
	s_barrier
	s_waitcnt vmcnt(0)
	ds_write_b128 v206, v[246:249] offset:23552
	ds_write_b128 v207, v[250:253] offset:11264
	buffer_load_dwordx4 v[238:241], v208, s[8:11], s93 offen
	buffer_load_dwordx4 v[242:245], v208, s[12:15], s28 offen
	s_add_u32 s93, s93, 0x2000
	s_add_u32 s28, s28, 0x2000
	s_cmp_ge_u32 s62, s24
	s_cbranch_scc0 .Ldf_s1_5
	s_cmp_lt_u32 s62, s25
	s_cbranch_scc1 .Ldf_fixa_5

; #define MFMA(a, b, c) __builtin_amdgcn_mfma_f32_32x32x16_bf16((a), (b), (c), 0, 0, 0)
; DI unsigned pk2(float lo, float hi) { f32x2 v = {lo, hi}; b16x2 r = __builtin_convertvector(v, b16x2); return __builtin_bit_cast(unsigned, r); }
; #define LDS_BARRIER() asm volatile("s_waitcnt lgkmcnt(0)\n\ts_barrier" ::: "memory")
; template <int MODE>
; DI void attn_item(const Params& p, int layer, int bh, int qb, char* lds) {
;     ...
;         auto smpass = [&]() {
;           ps = 0.f;
; #pragma unroll
;           for (int sub = 0; sub < 2; ++sub)
; #pragma unroll
;             for (int ks = 0; ks < 2; ++ks)
; #pragma unroll
;               for (int i = 0; i < 4; ++i) {
;                 const float p0 = __builtin_amdgcn_exp2f(s[sub][8 * ks + 2 * i]), p1 = __builtin_amdgcn_exp2f(s[sub][8 * ks + 2 * i + 1]);
;                 ps += p0 + p1; pk[mp][sub][ks][i] = pk2(p0, p1);
;               }
;         };
;         if (first) rebase();
;         smpass();
;         if (!first && __any(!(ps <= PSLIM))) { rebase(); smpass(); }
;         l[mp] += ps;
;         __builtin_amdgcn_sched_barrier(0);
;       }
; #pragma unroll
;       for (int sub = 0; sub < 2; ++sub) {
;         s16x4 vv[8];
;         if (NMAP == 1) {
; #pragma unroll
;           for (int i = 0; i < 8; ++i) vv[i] = vpre[sub * 8 + i];
;         } else {
;           if (sub == 0) trread8<0>(vaddr, vv); else trread8<32 * VSTR>(vaddr, vv);
;         }
;         __builtin_amdgcn_s_setprio(1);
; #pragma unroll
;         for (int ks = 0; ks < 2; ++ks) {
; #pragma unroll
;           for (int dt = 0; dt < 2; ++dt) {
;             s16x4 lo = vv[ks * 4 + dt * 2], hi = vv[ks * 4 + dt * 2 + 1];
;             bf16x8 vf = __builtin_shufflevector(lo, hi, 0, 1, 2, 3, 4, 5, 6, 7);
; #pragma unroll
;             for (int mp = 0; mp < NMAP; ++mp) O[mp][dt] = MFMA(vf, __builtin_bit_cast(bf16x8, pk[mp][sub][ks]), O[mp][dt]);
;           }
;         }
;         __builtin_amdgcn_s_setprio(0);
;         __builtin_amdgcn_sched_barrier(0);
;       }
;     ...
;   for (int t = 0; t < nt; t += 2) {
;     if (t + 2 < nt) gload(kt0 + t + 2, rkA, rvA);
;     compute(t, 0);
;     if (t + 1 < nt) lstore(1, rkB, rvB);
;     LDS_BARRIER();
;     if (t + 1 >= nt) break;
;     if (t + 3 < nt) gload(kt0 + t + 3, rkB, rvB);
;     compute(t + 1, 1);
;     if (t + 2 < nt) lstore(0, rkA, rvA);
;     LDS_BARRIER();
.Ldf_s2_5:
	ds_read_b64_tr_b16 v[222:223], v205 offset:54272
	ds_read_b64_tr_b16 v[224:225], v205 offset:55808
	ds_read_b64_tr_b16 v[226:227], v205 offset:54336
	ds_read_b64_tr_b16 v[228:229], v205 offset:55872
	ds_read_b128 v[230:233], v204 offset:2048
	v_exp_f32_e32 v6, v132
	v_exp_f32_e32 v7, v133
	v_exp_f32_e32 v186, v134
	v_exp_f32_e32 v187, v135
	s_waitcnt lgkmcnt(3)
	v_mfma_f32_32x32x16_bf16 v[56:71], v[222:225], v[164:167], v[56:71]
	ds_read_b64_tr_b16 v[234:235], v205 offset:57344
	ds_read_b64_tr_b16 v[236:237], v205 offset:58880
	v_add_f32_e32 v192, v6, v7
	s_waitcnt lgkmcnt(3)
	v_mfma_f32_32x32x16_bf16 v[24:39], v[226:229], v[164:167], v[24:39]
	ds_read_b64_tr_b16 v[222:223], v205 offset:57408
	ds_read_b64_tr_b16 v[224:225], v205 offset:58944
	v_cvt_pk_bf16_f32 v164, v6, v7
	v_add_f32_e32 v192, v192, v186
	v_add_f32_e32 v192, v192, v187
	v_cvt_pk_bf16_f32 v165, v186, v187
	v_exp_f32_e32 v188, v136
	v_exp_f32_e32 v189, v137
	v_exp_f32_e32 v190, v138
	s_waitcnt lgkmcnt(4)
	v_mfma_f32_32x32x16_bf16 v[88:103], v[230:233], v[0:3], v[72:87]
	ds_read_b128 v[226:229], v204 offset:2080
	v_exp_f32_e32 v191, v139
	v_add_f32_e32 v192, v192, v188
	v_add_f32_e32 v192, v192, v189
	v_cvt_pk_bf16_f32 v166, v188, v189
	v_add_f32_e32 v192, v192, v190
	v_add_f32_e32 v192, v192, v191
	v_cvt_pk_bf16_f32 v167, v190, v191
	s_waitcnt lgkmcnt(3)
	v_mfma_f32_32x32x16_bf16 v[56:71], v[234:237], v[172:175], v[56:71]
	ds_read_b64_tr_b16 v[230:231], v205 offset:60416
	ds_read_b64_tr_b16 v[232:233], v205 offset:61952
	v_exp_f32_e32 v6, v140
	v_exp_f32_e32 v7, v141
	v_exp_f32_e32 v186, v142
	v_exp_f32_e32 v187, v143
	v_add_f32_e32 v193, v6, v7
	s_waitcnt lgkmcnt(3)
	v_mfma_f32_32x32x16_bf16 v[24:39], v[222:225], v[172:175], v[24:39]
	ds_read_b64_tr_b16 v[234:235], v205 offset:60480
	ds_read_b64_tr_b16 v[236:237], v205 offset:62016
	v_cvt_pk_bf16_f32 v172, v6, v7
	v_add_f32_e32 v193, v193, v186
	v_add_f32_e32 v193, v193, v187
	v_cvt_pk_bf16_f32 v173, v186, v187
	v_exp_f32_e32 v188, v144
	v_exp_f32_e32 v189, v145
	v_exp_f32_e32 v190, v146
	s_waitcnt lgkmcnt(4)
	v_mfma_f32_32x32x16_bf16 v[88:103], v[226:229], v[120:123], v[88:103]
	ds_read_b128 v[222:225], v204 offset:6656
	v_exp_f32_e32 v191, v147
	v_add_f32_e32 v193, v193, v188
	v_add_f32_e32 v193, v193, v189
	v_cvt_pk_bf16_f32 v174, v188, v189
	v_add_f32_e32 v193, v193, v190
	v_add_f32_e32 v193, v193, v191
	v_cvt_pk_bf16_f32 v175, v190, v191
	s_waitcnt lgkmcnt(3)
	v_mfma_f32_32x32x16_bf16 v[56:71], v[230:233], v[176:179], v[56:71]
	ds_read_b64_tr_b16 v[226:227], v205 offset:63488
	ds_read_b64_tr_b16 v[228:229], v205 offset:65024
	v_exp_f32_e32 v6, v148
	v_exp_f32_e32 v7, v149
	v_exp_f32_e32 v186, v150
	v_exp_f32_e32 v187, v151
	v_add_f32_e32 v194, v6, v7
	s_waitcnt lgkmcnt(3)
	v_mfma_f32_32x32x16_bf16 v[24:39], v[234:237], v[176:179], v[24:39]
	ds_read_b64_tr_b16 v[230:231], v205 offset:63552
	ds_read_b64_tr_b16 v[232:233], v205 offset:65088
	v_cvt_pk_bf16_f32 v176, v6, v7
	v_add_f32_e32 v194, v194, v186
	v_add_f32_e32 v194, v194, v187
	v_cvt_pk_bf16_f32 v177, v186, v187
	v_exp_f32_e32 v188, v152
	v_exp_f32_e32 v189, v153
	v_exp_f32_e32 v190, v154
	s_waitcnt lgkmcnt(4)
	v_mfma_f32_32x32x16_bf16 v[104:119], v[222:225], v[0:3], v[72:87]
	ds_read_b128 v[234:237], v204 offset:6688
	v_exp_f32_e32 v191, v155
	v_add_f32_e32 v194, v194, v188
	v_add_f32_e32 v194, v194, v189
	v_cvt_pk_bf16_f32 v178, v188, v189
	v_add_f32_e32 v194, v194, v190
	v_add_f32_e32 v194, v194, v191
	v_cvt_pk_bf16_f32 v179, v190, v191
	s_waitcnt lgkmcnt(3)
	v_mfma_f32_32x32x16_bf16 v[56:71], v[226:229], v[180:183], v[56:71]
	v_exp_f32_e32 v6, v156
	v_exp_f32_e32 v7, v157
	v_exp_f32_e32 v186, v158
	v_exp_f32_e32 v187, v159
	v_add_f32_e32 v195, v6, v7
	s_waitcnt lgkmcnt(1)
	v_mfma_f32_32x32x16_bf16 v[24:39], v[230:233], v[180:183], v[24:39]
	v_cvt_pk_bf16_f32 v180, v6, v7
	v_add_f32_e32 v195, v195, v186
	v_add_f32_e32 v195, v195, v187
	v_cvt_pk_bf16_f32 v181, v186, v187
	v_exp_f32_e32 v188, v160
	v_exp_f32_e32 v189, v161
	v_exp_f32_e32 v190, v162
	s_waitcnt lgkmcnt(0)
	v_mfma_f32_32x32x16_bf16 v[104:119], v[234:237], v[120:123], v[104:119]
	v_exp_f32_e32 v191, v163
	v_add_f32_e32 v195, v195, v188
	v_add_f32_e32 v195, v195, v189
	v_cvt_pk_bf16_f32 v182, v188, v189
	v_add_f32_e32 v195, v195, v190
	v_add_f32_e32 v195, v195, v191
	v_cvt_pk_bf16_f32 v183, v190, v191
	v_add_f32_e32 v192, v192, v193
	v_add_f32_e32 v194, v194, v195
	v_add_f32_e32 v192, v192, v194
	v_add_f32_e32 v171, v171, v192
	v_max_f32_e32 v201, v201, v192
	s_add_u32 s62, s62, 1
	s_waitcnt lgkmcnt(0)
	s_barrier
	s_branch .Ldf_loop
; #define MFMA(a, b, c) __builtin_amdgcn_mfma_f32_32x32x16_bf16((a), (b), (c), 0, 0, 0)
; DI u16 f2bf(float x) { unsigned u = __float_as_uint(x); u += 0x7fffu + ((u >> 16) & 1u); return (u16)(u >> 16); }
; DI float bf2f(u16 b) { return __uint_as_float(((unsigned)b) << 16); }
; template <int MODE>
; DI void attn_item(const Params& p, int layer, int bh, int qb, char* lds) {
;     ...
;   auto set_c0 = [&](float c0) {
;     const unsigned hi = f2bf(c0); const unsigned lo = f2bf(c0 - bf2f((u16)hi));
;     u32x4 tq = {hh == 0 ? (hi | (lo << 16)) : 0u, 0u, 0u, 0u}; qaug = __builtin_bit_cast(bf16x8, tq);
;     { const f32x16 z16 = {0.f, 0.f, 0.f, 0.f, 0.f, 0.f, 0.f, 0.f, 0.f, 0.f, 0.f, 0.f, 0.f, 0.f, 0.f, 0.f}; c0p = MFMA(kaug, qaug, z16); }
;   };
;   int c0cls = -1;
;   auto compute = [&](const int t, const int cur) {
;     const int k0 = (kt0 + t) * 64;
;     const char* Ks = stage0 + cur * STAGE;
;     bool active = true;
;     if (MODE == 2) active = (k0 + 63 >= q0w - 128) && (k0 <= q0w + 159);
;     if (active) {
;       const float* brow = brel + (k0 - q0w - l32 + 4 * hh + 224);
;       int cls = 0; float cb = 0.f;
;       if (MODE == 1) {
;         const int rmax = k0 + 63 - q0w, rmin = k0 - (q0w + 31);
;         if (rmax <= -128) { cls = 1; cb = brel[224 - 128]; }
;         else if (rmin >= 128) { cls = 2; cb = brel[224 + 128]; }
;       }
;       const bool far = cls != 0;
;       if (cls != c0cls) { c0cls = cls; set_c0(cb - m); }
;     ...
;         if (MODE != 0 && !far) {
; #pragma unroll
;           for (int sub = 0; sub < 2; ++sub)
; #pragma unroll
;             for (int r = 0; r < 16; ++r) s[sub][r] += brow[32 * sub + (r & 3) + 8 * (r >> 2)];
;         }
.Ldf_fixa_0:
	s_nop 11
	s_lshl_b32 s5, s62, 8
	v_add_u32_e32 v196, s5, v209
	ds_read2_b32 v[222:223], v196 offset0:0 offset1:1
	ds_read2_b32 v[224:225], v196 offset0:2 offset1:3
	ds_read2_b32 v[226:227], v196 offset0:8 offset1:9
	ds_read2_b32 v[228:229], v196 offset0:10 offset1:11
	ds_read2_b32 v[230:231], v196 offset0:16 offset1:17
	ds_read2_b32 v[232:233], v196 offset0:18 offset1:19
	ds_read2_b32 v[234:235], v196 offset0:24 offset1:25
	ds_read2_b32 v[236:237], v196 offset0:26 offset1:27
	s_waitcnt lgkmcnt(0)
	v_add_f32_e32 v88, v88, v222
	v_add_f32_e32 v89, v89, v223
	v_add_f32_e32 v90, v90, v224
	v_add_f32_e32 v91, v91, v225
	v_add_f32_e32 v92, v92, v226
	v_add_f32_e32 v93, v93, v227
	v_add_f32_e32 v94, v94, v228
	v_add_f32_e32 v95, v95, v229
	v_add_f32_e32 v96, v96, v230
	v_add_f32_e32 v97, v97, v231
	v_add_f32_e32 v98, v98, v232
	v_add_f32_e32 v99, v99, v233
	v_add_f32_e32 v100, v100, v234
	v_add_f32_e32 v101, v101, v235
	v_add_f32_e32 v102, v102, v236
	v_add_f32_e32 v103, v103, v237
	ds_read2_b32 v[222:223], v196 offset0:32 offset1:33
	ds_read2_b32 v[224:225], v196 offset0:34 offset1:35
	ds_read2_b32 v[226:227], v196 offset0:40 offset1:41
	ds_read2_b32 v[228:229], v196 offset0:42 offset1:43
	ds_read2_b32 v[230:231], v196 offset0:48 offset1:49
	ds_read2_b32 v[232:233], v196 offset0:50 offset1:51
	ds_read2_b32 v[234:235], v196 offset0:56 offset1:57
	ds_read2_b32 v[236:237], v196 offset0:58 offset1:59
	s_waitcnt lgkmcnt(0)
	v_add_f32_e32 v104, v104, v222
	v_add_f32_e32 v105, v105, v223
	v_add_f32_e32 v106, v106, v224
	v_add_f32_e32 v107, v107, v225
	v_add_f32_e32 v108, v108, v226
	v_add_f32_e32 v109, v109, v227
	v_add_f32_e32 v110, v110, v228
	v_add_f32_e32 v111, v111, v229
	v_add_f32_e32 v112, v112, v230
	v_add_f32_e32 v113, v113, v231
	v_add_f32_e32 v114, v114, v232
	v_add_f32_e32 v115, v115, v233
	v_add_f32_e32 v116, v116, v234
	v_add_f32_e32 v117, v117, v235
	v_add_f32_e32 v118, v118, v236
	v_add_f32_e32 v119, v119, v237
	s_branch .Ldf_s1_0
.Ldf_c0n_0:
	s_nop 11
	v_sub_f32_e32 v198, 0, v200
	v_bfe_u32 v197, v198, 16, 1
	v_add3_u32 v196, v198, v197, s45
	v_lshrrev_b32_e32 v197, 16, v196
	v_and_b32_e32 v196, 0xffff0000, v196
	v_sub_f32_e32 v196, v198, v196
	v_bfe_u32 v198, v196, 16, 1
	v_add3_u32 v196, v196, v198, s45
	v_and_or_b32 v196, v196, s92, v197
	v_cndmask_b32_e64 v226, 0, v196, s[6:7]
	v_mov_b32_e32 v196, 0x3f803f80
	v_cndmask_b32_e64 v222, 0, v196, s[6:7]
	v_mov_b32_e32 v223, 0
	v_mov_b32_e32 v227, 0
	v_mov_b32_e32 v224, 0
	v_mov_b32_e32 v228, 0
	v_mov_b32_e32 v225, 0
	v_mov_b32_e32 v229, 0
	s_nop 1
	v_mfma_f32_32x32x16_bf16 v[72:87], v[222:225], v[226:229], 0
	s_nop 11
	s_branch .Ldf_c0d_0
.Ldf_c0r_0:
	s_nop 11
	v_sub_f32_e32 v198, v211, v200
	v_bfe_u32 v197, v198, 16, 1
	v_add3_u32 v196, v198, v197, s45
	v_lshrrev_b32_e32 v197, 16, v196
	v_and_b32_e32 v196, 0xffff0000, v196
	v_sub_f32_e32 v196, v198, v196
	v_bfe_u32 v198, v196, 16, 1
	v_add3_u32 v196, v196, v198, s45
	v_and_or_b32 v196, v196, s92, v197
	v_cndmask_b32_e64 v226, 0, v196, s[6:7]
	v_mov_b32_e32 v196, 0x3f803f80
	v_cndmask_b32_e64 v222, 0, v196, s[6:7]
	v_mov_b32_e32 v223, 0
	v_mov_b32_e32 v227, 0
	v_mov_b32_e32 v224, 0
	v_mov_b32_e32 v228, 0
	v_mov_b32_e32 v225, 0
	v_mov_b32_e32 v229, 0
	s_nop 1
	v_mfma_f32_32x32x16_bf16 v[72:87], v[222:225], v[226:229], 0
	s_nop 11
	s_branch .Ldf_c0d_0
.Ldf_fixb_0:
	s_nop 11
	s_lshl_b32 s5, s62, 8
	v_add_u32_e32 v196, s5, v209
	ds_read2_b32 v[222:223], v196 offset0:0 offset1:1
	ds_read2_b32 v[224:225], v196 offset0:2 offset1:3
	ds_read2_b32 v[226:227], v196 offset0:8 offset1:9
	ds_read2_b32 v[228:229], v196 offset0:10 offset1:11
	ds_read2_b32 v[230:231], v196 offset0:16 offset1:17
	ds_read2_b32 v[232:233], v196 offset0:18 offset1:19
	ds_read2_b32 v[234:235], v196 offset0:24 offset1:25
	ds_read2_b32 v[236:237], v196 offset0:26 offset1:27
	s_waitcnt lgkmcnt(0)
	v_add_f32_e32 v132, v132, v222
	v_add_f32_e32 v133, v133, v223
	v_add_f32_e32 v134, v134, v224
	v_add_f32_e32 v135, v135, v225
	v_add_f32_e32 v136, v136, v226
	v_add_f32_e32 v137, v137, v227
	v_add_f32_e32 v138, v138, v228
	v_add_f32_e32 v139, v139, v229
	v_add_f32_e32 v140, v140, v230
	v_add_f32_e32 v141, v141, v231
	v_add_f32_e32 v142, v142, v232
	v_add_f32_e32 v143, v143, v233
	v_add_f32_e32 v144, v144, v234
	v_add_f32_e32 v145, v145, v235
	v_add_f32_e32 v146, v146, v236
	v_add_f32_e32 v147, v147, v237
	ds_read2_b32 v[222:223], v196 offset0:32 offset1:33
	ds_read2_b32 v[224:225], v196 offset0:34 offset1:35
	ds_read2_b32 v[226:227], v196 offset0:40 offset1:41
	ds_read2_b32 v[228:229], v196 offset0:42 offset1:43
	ds_read2_b32 v[230:231], v196 offset0:48 offset1:49
	ds_read2_b32 v[232:233], v196 offset0:50 offset1:51
	ds_read2_b32 v[234:235], v196 offset0:56 offset1:57
	ds_read2_b32 v[236:237], v196 offset0:58 offset1:59
	s_waitcnt lgkmcnt(0)
	v_add_f32_e32 v148, v148, v222
	v_add_f32_e32 v149, v149, v223
	v_add_f32_e32 v150, v150, v224
	v_add_f32_e32 v151, v151, v225
	v_add_f32_e32 v152, v152, v226
	v_add_f32_e32 v153, v153, v227
	v_add_f32_e32 v154, v154, v228
	v_add_f32_e32 v155, v155, v229
	v_add_f32_e32 v156, v156, v230
	v_add_f32_e32 v157, v157, v231
	v_add_f32_e32 v158, v158, v232
	v_add_f32_e32 v159, v159, v233
	v_add_f32_e32 v160, v160, v234
	v_add_f32_e32 v161, v161, v235
	v_add_f32_e32 v162, v162, v236
	v_add_f32_e32 v163, v163, v237
	s_branch .Ldf_s2_0

; #define MFMA(a, b, c) __builtin_amdgcn_mfma_f32_32x32x16_bf16((a), (b), (c), 0, 0, 0)
; #define LDS_BARRIER() asm volatile("s_waitcnt lgkmcnt(0)\n\ts_barrier" ::: "memory")
; template <int MODE>
; DI void attn_item(const Params& p, int layer, int bh, int qb, char* lds) {
;     ...
; #pragma unroll
;       for (int sub = 0; sub < 2; ++sub) {
;         s16x4 vv[8];
;         if (NMAP == 1) {
; #pragma unroll
;           for (int i = 0; i < 8; ++i) vv[i] = vpre[sub * 8 + i];
;         } else {
;           if (sub == 0) trread8<0>(vaddr, vv); else trread8<32 * VSTR>(vaddr, vv);
;         }
;         __builtin_amdgcn_s_setprio(1);
; #pragma unroll
;         for (int ks = 0; ks < 2; ++ks) {
; #pragma unroll
;           for (int dt = 0; dt < 2; ++dt) {
;             s16x4 lo = vv[ks * 4 + dt * 2], hi = vv[ks * 4 + dt * 2 + 1];
;             bf16x8 vf = __builtin_shufflevector(lo, hi, 0, 1, 2, 3, 4, 5, 6, 7);
; #pragma unroll
;             for (int mp = 0; mp < NMAP; ++mp) O[mp][dt] = MFMA(vf, __builtin_bit_cast(bf16x8, pk[mp][sub][ks]), O[mp][dt]);
;           }
;         }
;         __builtin_amdgcn_s_setprio(0);
;         __builtin_amdgcn_sched_barrier(0);
;       }
;     ...
;   for (int t = 0; t < nt; t += 2) {
;     if (t + 2 < nt) gload(kt0 + t + 2, rkA, rvA);
;     compute(t, 0);
;     if (t + 1 < nt) lstore(1, rkB, rvB);
;     LDS_BARRIER();
;     if (t + 1 >= nt) break;
;     if (t + 3 < nt) gload(kt0 + t + 3, rkB, rvB);
;     compute(t + 1, 1);
;     if (t + 2 < nt) lstore(0, rkA, rvA);
;     LDS_BARRIER();
;   }
;   __syncthreads();
.Ldf_exit:
	s_waitcnt vmcnt(0)
	ds_read_b64_tr_b16 v[222:223], v205 offset:32768
	ds_read_b64_tr_b16 v[224:225], v205 offset:34304
	s_waitcnt lgkmcnt(0)
	v_mfma_f32_32x32x16_bf16 v[40:55], v[222:225], v[164:167], v[40:55]
	ds_read_b64_tr_b16 v[226:227], v205 offset:32832
	ds_read_b64_tr_b16 v[228:229], v205 offset:34368
	s_waitcnt lgkmcnt(0)
	v_mfma_f32_32x32x16_bf16 v[8:23], v[226:229], v[164:167], v[8:23]
	ds_read_b64_tr_b16 v[230:231], v205 offset:35840
	ds_read_b64_tr_b16 v[232:233], v205 offset:37376
	s_waitcnt lgkmcnt(0)
	v_mfma_f32_32x32x16_bf16 v[40:55], v[230:233], v[172:175], v[40:55]
	ds_read_b64_tr_b16 v[234:235], v205 offset:35904
	ds_read_b64_tr_b16 v[236:237], v205 offset:37440
	s_waitcnt lgkmcnt(0)
	v_mfma_f32_32x32x16_bf16 v[8:23], v[234:237], v[172:175], v[8:23]
	ds_read_b64_tr_b16 v[222:223], v205 offset:38912
	ds_read_b64_tr_b16 v[224:225], v205 offset:40448
	s_waitcnt lgkmcnt(0)
	v_mfma_f32_32x32x16_bf16 v[40:55], v[222:225], v[176:179], v[40:55]
	ds_read_b64_tr_b16 v[226:227], v205 offset:38976
	ds_read_b64_tr_b16 v[228:229], v205 offset:40512
	s_waitcnt lgkmcnt(0)
	v_mfma_f32_32x32x16_bf16 v[8:23], v[226:229], v[176:179], v[8:23]
	ds_read_b64_tr_b16 v[230:231], v205 offset:41984
	ds_read_b64_tr_b16 v[232:233], v205 offset:43520
	s_waitcnt lgkmcnt(0)
	v_mfma_f32_32x32x16_bf16 v[40:55], v[230:233], v[180:183], v[40:55]
	ds_read_b64_tr_b16 v[234:235], v205 offset:42048
	ds_read_b64_tr_b16 v[236:237], v205 offset:43584
	s_waitcnt lgkmcnt(0)
	v_mfma_f32_32x32x16_bf16 v[8:23], v[234:237], v[180:183], v[8:23]
	v_cmp_nge_f32_e32 vcc, s94, v201
	s_nop 0
	s_cmp_lg_u64 vcc, 0
	s_cselect_b32 s5, 1, 0
	v_mov_b32_e32 v196, s5
	v_lshrrev_b32_e32 v197, 6, v184
	v_lshlrev_b32_e32 v197, 2, v197
	v_add_u32_e32 v197, 66560, v197
	ds_write_b32 v197, v196
	s_waitcnt lgkmcnt(0)
	s_barrier
	v_mov_b32_e32 v197, 66560
	ds_read_b128 v[222:225], v197
	ds_read_b128 v[226:229], v197 offset:16
	s_waitcnt lgkmcnt(0)
	v_or3_b32 v196, v222, v223, v224
	v_or3_b32 v196, v196, v225, v226
	v_or3_b32 v196, v196, v227, v228
	v_or_b32_e32 v196, v196, v229
	s_nop 0
	v_readfirstlane_b32 s5, v196
	s_nop 11
	s_cmp_lg_u32 s5, 0
	s_cbranch_scc0 .LBB0_505
	s_barrier
	v_mov_b32_e32 v6, v184
	s_and_b32 s20, s60, 3
	s_lshl_b32 s23, s60, 5
	s_and_b32 s23, s23, 0x1f00
	s_mov_b64 s[4:5], -1
	s_mov_b64 s[8:9], -1
	s_branch .Ldiff_slow
